# v10: v8 + P11 deferred last epilogue (overlaps next tile ds_read latency), flag in s98, flush at loop exits
# speedup vs baseline: 1.0003x; 1.0003x over previous
; #define LAS __attribute__((address_space(3)))
; DI size_t sc_row_off(int b, int s) { const int qb = s >> 7; return ((size_t)(b * 2080 + ((qb * (qb + 1)) >> 1))) * 16384 + (size_t)(s & 127) * ((qb + 1) * 128); }
; DI void indexer_tile(const LAS unsigned char* buf, const f16x8 (&af)[2][8], const f32x4 (&wv)[2][4], float* sc0, float* sc1, int kt, int r32, int h2) {
;     ...
;         f32x2_t a0 = {0.f, 0.f}, a1 = {0.f, 0.f};
; #pragma unroll
;         for (int q = 0; q < 4; ++q)
; #pragma unroll
;             for (int e = 0; e < 4; e += 2) {
;                 const f32x2_t r0 = {relu1(c0[4 * q + e]), relu1(c0[4 * q + e + 1])};
;                 const f32x2_t r1 = {relu1(c1[4 * q + e]), relu1(c1[4 * q + e + 1])};
;                 const f32x2_t w0 = {wv[0][q][e], wv[0][q][e + 1]}, w1 = {wv[1][q][e], wv[1][q][e + 1]};
;                 a0 = __builtin_elementwise_fma(r0, w0, a0); a1 = __builtin_elementwise_fma(r1, w1, a1); }
;         float s0 = a0.x + a0.y, s1 = a1.x + a1.y;
;         s0 += __shfl_xor(s0, 32); s1 += __shfl_xor(s1, 32);
;         if (h2 == 0) { sc0[kt * 64 + 32 * sub + r32] = s0; sc1[kt * 64 + 32 * sub + r32] = s1; }
; DI void indexer_phase(const unsigned short* QI, const unsigned short* KI16, const float* WI, float* SC, LAS unsigned char* lds, int tid, int bid, int G) {
;     ...
;             float* sc0 = SC + sc_row_off(b, tb + 2 * w); float* sc1 = SC + sc_row_off(b, tb + 2 * w + 1);
;             const unsigned short* src = KI16 + (size_t)b * SEQ * 128 + (size_t)key0 * 128 + ch * 8;
;             u32x4 a0, a1, b0 = {0u, 0u, 0u, 0u}, b1 = {0u, 0u, 0u, 0u};
;             a0 = *(const u32x4*)src; a1 = *(const u32x4*)(src + 32 * 128);
;             if (nt > 1) { b0 = *(const u32x4*)(src + 64 * 128); b1 = *(const u32x4*)(src + 96 * 128); }
;             __syncthreads();
;             *(LAS u32x4*)(buf0 + key0 * KT_ROWB + ch * 16) = a0; *(LAS u32x4*)(buf0 + (key0 + 32) * KT_ROWB + ch * 16) = a1;
;             __syncthreads();
.LBB0_1822:
	s_add_i32 s6, s43, s36
	s_ashr_i32 s7, s6, 7
	s_add_i32 s8, s7, 1
	s_mul_i32 s7, s8, s7
	s_and_b32 s9, s6, 0x7e
	s_ashr_i32 s10, s7, 1
	s_lshl_b32 s8, s8, 7
	s_or_b32 s11, s9, 1
	s_cmp_gt_i32 s41, -1
	s_mul_hi_i32 s7, s8, s9
	s_mul_i32 s6, s8, s9
	s_mul_hi_i32 s9, s8, s11
	s_mul_i32 s8, s8, s11
	s_cselect_b64 s[14:15], -1, 0
	s_cmp_lt_i32 s41, 0
	s_barrier
	s_waitcnt vmcnt(1)
	ds_write_b128 v209, v[132:135]
	s_waitcnt vmcnt(0)
	ds_write_b128 v209, v[136:139] offset:8704
	s_waitcnt lgkmcnt(0)
	s_barrier
	s_cbranch_scc1 .LBB0_1843
	s_ashr_i32 s11, s10, 31
	s_lshl_b64 s[18:19], s[10:11], 16
	s_add_u32 s11, s17, s18
	s_addc_u32 s22, s33, s19
	s_lshl_b64 s[18:19], s[6:7], 2
	s_add_u32 s18, s11, s18
	s_addc_u32 s19, s22, s19
	s_lshl_b64 s[20:21], s[8:9], 2
	s_add_u32 s20, s11, s20
	s_addc_u32 s21, s22, s21
	s_mov_b32 s11, 3
	v_mov_b32_e32 v32, v206
	v_mov_b64_e32 v[34:35], v[200:201]
	s_mov_b32 s98, 0
	s_branch .LBB0_1825
.Lp11_fb0:
	v_max_i32_e32 v0, 0, v0
	v_max_i32_e32 v1, 0, v1
	v_fma_f32 v243, v0, v116, 0
	v_fma_f32 v244, v1, v117, 0
	v_max_i32_e32 v2, 0, v2
	v_max_i32_e32 v3, 0, v3
	v_fma_f32 v243, v2, v118, v243
	v_fma_f32 v244, v3, v119, v244
	v_max_i32_e32 v4, 0, v4
	v_max_i32_e32 v5, 0, v5
	v_fma_f32 v243, v4, v120, v243
	v_fma_f32 v244, v5, v121, v244
	v_max_i32_e32 v6, 0, v6
	v_max_i32_e32 v7, 0, v7
	v_fma_f32 v243, v6, v122, v243
	v_fma_f32 v244, v7, v123, v244
	v_max_i32_e32 v8, 0, v8
	v_max_i32_e32 v9, 0, v9
	v_fma_f32 v243, v8, v124, v243
	v_fma_f32 v244, v9, v125, v244
	v_max_i32_e32 v10, 0, v10
	v_max_i32_e32 v11, 0, v11
	v_fma_f32 v243, v10, v126, v243
	v_fma_f32 v244, v11, v127, v244
	v_max_i32_e32 v12, 0, v12
	v_max_i32_e32 v13, 0, v13
	v_fma_f32 v243, v12, v128, v243
	v_fma_f32 v244, v13, v129, v244
	v_max_i32_e32 v14, 0, v14
	v_max_i32_e32 v15, 0, v15
	v_fma_f32 v243, v14, v130, v243
	v_fma_f32 v244, v15, v131, v244
	v_add_f32_e32 v245, v243, v244
	v_mov_b32_e32 v246, v245
	v_lshlrev_b32_e32 v247, 2, v32
	s_nop 0
	v_permlane32_swap_b32_e32 v246, v245
	v_add_f32_e32 v246, v246, v245
	s_mov_b64 exec, s[4:5]
	global_store_dword v247, v246, s[20:21] offset:-128
	s_mov_b64 exec, -1
	s_mov_b32 s98, 0
	s_branch .LBB0_1843

; #define LAS __attribute__((address_space(3)))
; DI void indexer_tile(const LAS unsigned char* buf, const f16x8 (&af)[2][8], const f32x4 (&wv)[2][4], float* sc0, float* sc1, int kt, int r32, int h2) {
;     ...
;     f16x8 bfr[2][8];
; #pragma unroll
;     for (int sub = 0; sub < 2; ++sub)
; #pragma unroll
;         for (int ks = 0; ks < 8; ++ks) bfr[sub][ks] = *(const LAS f16x8*)(buf + (32 * sub + r32) * KT_ROWB + (16 * ks + 8 * h2) * 2);
;     __builtin_amdgcn_sched_barrier(0);
; #pragma unroll
;     for (int sub = 0; sub < 2; ++sub) {
;         f32x16 c0, c1;
; #pragma unroll
;         for (int i = 0; i < 16; ++i) { c0[i] = 0.f; c1[i] = 0.f; }
; #pragma unroll
;         for (int ks = 0; ks < 8; ++ks) { c0 = __builtin_amdgcn_mfma_f32_32x32x16_f16(af[0][ks], bfr[sub][ks], c0, 0, 0, 0); c1 = __builtin_amdgcn_mfma_f32_32x32x16_f16(af[1][ks], bfr[sub][ks], c1, 0, 0, 0); }
;         f32x2_t a0 = {0.f, 0.f}, a1 = {0.f, 0.f};
; #pragma unroll
;         for (int q = 0; q < 4; ++q)
; #pragma unroll
;             for (int e = 0; e < 4; e += 2) {
;                 const f32x2_t r0 = {relu1(c0[4 * q + e]), relu1(c0[4 * q + e + 1])};
;                 const f32x2_t r1 = {relu1(c1[4 * q + e]), relu1(c1[4 * q + e + 1])};
;                 const f32x2_t w0 = {wv[0][q][e], wv[0][q][e + 1]}, w1 = {wv[1][q][e], wv[1][q][e + 1]};
;                 a0 = __builtin_elementwise_fma(r0, w0, a0); a1 = __builtin_elementwise_fma(r1, w1, a1); }
;         float s0 = a0.x + a0.y, s1 = a1.x + a1.y;
;         s0 += __shfl_xor(s0, 32); s1 += __shfl_xor(s1, 32);
;         if (h2 == 0) { sc0[kt * 64 + 32 * sub + r32] = s0; sc1[kt * 64 + 32 * sub + r32] = s1; }
; DI void indexer_phase(const unsigned short* QI, const unsigned short* KI16, const float* WI, float* SC, LAS unsigned char* lds, int tid, int bid, int G) {
;     ...
;             for (int kt = 0; kt < nt; kt += 2) {
;                 if (kt + 2 < nt) { const unsigned short* p = src + (size_t)(kt + 2) * 64 * 128; a0 = *(const u32x4*)p; a1 = *(const u32x4*)(p + 32 * 128); }
;                 indexer_tile(buf0, af, wv, sc0, sc1, kt, r32, h2);
.LBB0_1825:
	s_add_i32 s26, s11, -1
	s_cmp_le_i32 s26, s41
	s_cselect_b64 s[22:23], -1, 0
	s_cmp_gt_i32 s26, s41
	s_cbranch_scc1 .LBB0_1827
	v_add_co_u32_e32 v238, vcc, 0xffffa000, v34
	s_nop 1
	v_addc_co_u32_e32 v239, vcc, -1, v35, vcc
	v_add_co_u32_e32 v240, vcc, 0xffffc000, v34
	s_nop 1
	v_addc_co_u32_e32 v241, vcc, -1, v35, vcc
	global_load_dwordx4 v[132:135], v[238:239], off
	global_load_dwordx4 v[136:139], v[240:241], off
.LBB0_1827:
	ds_read_b128 v[250:253], v207
	ds_read_b128 v[210:213], v207 offset:32
	ds_read_b128 v[214:217], v207 offset:64
	ds_read_b128 v[218:221], v207 offset:96
	ds_read_b128 v[222:225], v207 offset:128
	ds_read_b128 v[226:229], v207 offset:160
	ds_read_b128 v[230:233], v207 offset:192
	ds_read_b128 v[234:237], v207 offset:224
	ds_read_b128 v[176:179], v207 offset:8704
	ds_read_b128 v[172:175], v207 offset:8736
	ds_read_b128 v[168:171], v207 offset:8768
	ds_read_b128 v[164:167], v207 offset:8800
	ds_read_b128 v[160:163], v207 offset:8832
	ds_read_b128 v[156:159], v207 offset:8864
	ds_read_b128 v[152:155], v207 offset:8896
	ds_read_b128 v[148:151], v207 offset:8928
	s_cmp_eq_u32 s98, 0
	s_cbranch_scc1 .Lp11_skip0
	v_max_i32_e32 v0, 0, v0
	v_max_i32_e32 v1, 0, v1
	v_fma_f32 v243, v0, v116, 0
	v_fma_f32 v244, v1, v117, 0
	v_max_i32_e32 v2, 0, v2
	v_max_i32_e32 v3, 0, v3
	v_fma_f32 v243, v2, v118, v243
	v_fma_f32 v244, v3, v119, v244
	v_max_i32_e32 v4, 0, v4
	v_max_i32_e32 v5, 0, v5
	v_fma_f32 v243, v4, v120, v243
	v_fma_f32 v244, v5, v121, v244
	v_max_i32_e32 v6, 0, v6
	v_max_i32_e32 v7, 0, v7
	v_fma_f32 v243, v6, v122, v243
	v_fma_f32 v244, v7, v123, v244
	v_max_i32_e32 v8, 0, v8
	v_max_i32_e32 v9, 0, v9
	v_fma_f32 v243, v8, v124, v243
	v_fma_f32 v244, v9, v125, v244
	v_max_i32_e32 v10, 0, v10
	v_max_i32_e32 v11, 0, v11
	v_fma_f32 v243, v10, v126, v243
	v_fma_f32 v244, v11, v127, v244
	v_max_i32_e32 v12, 0, v12
	v_max_i32_e32 v13, 0, v13
	v_fma_f32 v243, v12, v128, v243
	v_fma_f32 v244, v13, v129, v244
	v_max_i32_e32 v14, 0, v14
	v_max_i32_e32 v15, 0, v15
	v_fma_f32 v243, v14, v130, v243
	v_fma_f32 v244, v15, v131, v244
	v_add_f32_e32 v245, v243, v244
	v_mov_b32_e32 v246, v245
	v_lshlrev_b32_e32 v247, 2, v32
	s_nop 0
	v_permlane32_swap_b32_e32 v246, v245
	v_add_f32_e32 v246, v246, v245
	s_mov_b64 exec, s[4:5]
	global_store_dword v247, v246, s[20:21] offset:-128
	s_mov_b64 exec, -1
.Lp11_skip0:
	s_waitcnt lgkmcnt(15)
	v_mfma_f32_32x32x16_f16 v[16:31], v[36:39], v[250:253], 0
	s_waitcnt lgkmcnt(14)
	v_mfma_f32_32x32x16_f16 v[16:31], v[40:43], v[210:213], v[16:31]
	s_waitcnt lgkmcnt(13)
	v_mfma_f32_32x32x16_f16 v[16:31], v[44:47], v[214:217], v[16:31]
	s_waitcnt lgkmcnt(12)
	v_mfma_f32_32x32x16_f16 v[16:31], v[48:51], v[218:221], v[16:31]
	s_waitcnt lgkmcnt(11)
	v_mfma_f32_32x32x16_f16 v[16:31], v[52:55], v[222:225], v[16:31]
	s_waitcnt lgkmcnt(10)
	v_mfma_f32_32x32x16_f16 v[16:31], v[56:59], v[226:229], v[16:31]
	s_waitcnt lgkmcnt(9)
	v_mfma_f32_32x32x16_f16 v[16:31], v[60:63], v[230:233], v[16:31]
	s_waitcnt lgkmcnt(8)
	v_mfma_f32_32x32x16_f16 v[16:31], v[64:67], v[234:237], v[16:31]
	v_mfma_f32_32x32x16_f16 v[0:15], v[84:87], v[250:253], 0
	v_mfma_f32_32x32x16_f16 v[0:15], v[88:91], v[210:213], v[0:15]
	v_mfma_f32_32x32x16_f16 v[0:15], v[92:95], v[214:217], v[0:15]
	s_nop 8
	v_max_i32_e32 v16, 0, v16
	v_max_i32_e32 v17, 0, v17
	v_fma_f32 v238, v16, v68, 0
	v_fma_f32 v239, v17, v69, 0
	v_max_i32_e32 v18, 0, v18
	v_max_i32_e32 v19, 0, v19
	v_fma_f32 v238, v18, v70, v238
	v_mfma_f32_32x32x16_f16 v[0:15], v[96:99], v[218:221], v[0:15]
	v_fma_f32 v239, v19, v71, v239
	v_max_i32_e32 v20, 0, v20
	v_max_i32_e32 v21, 0, v21
	v_fma_f32 v238, v20, v72, v238
	v_fma_f32 v239, v21, v73, v239
	v_max_i32_e32 v22, 0, v22
	v_max_i32_e32 v23, 0, v23
	v_mfma_f32_32x32x16_f16 v[0:15], v[100:103], v[222:225], v[0:15]
	v_fma_f32 v238, v22, v74, v238
	v_fma_f32 v239, v23, v75, v239
	v_max_i32_e32 v24, 0, v24
	v_max_i32_e32 v25, 0, v25
	v_fma_f32 v238, v24, v76, v238
	v_fma_f32 v239, v25, v77, v239
	v_mfma_f32_32x32x16_f16 v[0:15], v[104:107], v[226:229], v[0:15]
	v_max_i32_e32 v26, 0, v26
	v_max_i32_e32 v27, 0, v27
	v_fma_f32 v238, v26, v78, v238
	v_fma_f32 v239, v27, v79, v239
	v_max_i32_e32 v28, 0, v28
	v_max_i32_e32 v29, 0, v29
	v_mfma_f32_32x32x16_f16 v[0:15], v[108:111], v[230:233], v[0:15]
	v_fma_f32 v238, v28, v80, v238
	v_fma_f32 v239, v29, v81, v239
	v_max_i32_e32 v30, 0, v30
	v_max_i32_e32 v31, 0, v31
	v_fma_f32 v238, v30, v82, v238
	v_fma_f32 v239, v31, v83, v239
	v_mfma_f32_32x32x16_f16 v[0:15], v[112:115], v[234:237], v[0:15]
	v_add_f32_e32 v240, v238, v239
	v_mov_b32_e32 v241, v240
	v_lshlrev_b32_e32 v242, 2, v32
	s_nop 0
	v_permlane32_swap_b32_e32 v241, v240
	v_add_f32_e32 v241, v241, v240
	s_mov_b64 exec, s[4:5]
	global_store_dword v242, v241, s[18:19]
	s_mov_b64 exec, -1
	s_waitcnt lgkmcnt(0)
; #define LAS __attribute__((address_space(3)))
; DI void indexer_tile(const LAS unsigned char* buf, const f16x8 (&af)[2][8], const f32x4 (&wv)[2][4], float* sc0, float* sc1, int kt, int r32, int h2) {
;     ...
;         f32x2_t a0 = {0.f, 0.f}, a1 = {0.f, 0.f};
; #pragma unroll
;         for (int q = 0; q < 4; ++q)
; #pragma unroll
;             for (int e = 0; e < 4; e += 2) {
;                 const f32x2_t r0 = {relu1(c0[4 * q + e]), relu1(c0[4 * q + e + 1])};
;                 const f32x2_t r1 = {relu1(c1[4 * q + e]), relu1(c1[4 * q + e + 1])};
;                 const f32x2_t w0 = {wv[0][q][e], wv[0][q][e + 1]}, w1 = {wv[1][q][e], wv[1][q][e + 1]};
;                 a0 = __builtin_elementwise_fma(r0, w0, a0); a1 = __builtin_elementwise_fma(r1, w1, a1); }
;         float s0 = a0.x + a0.y, s1 = a1.x + a1.y;
;         s0 += __shfl_xor(s0, 32); s1 += __shfl_xor(s1, 32);
;         if (h2 == 0) { sc0[kt * 64 + 32 * sub + r32] = s0; sc1[kt * 64 + 32 * sub + r32] = s1; }
; DI void indexer_phase(const unsigned short* QI, const unsigned short* KI16, const float* WI, float* SC, LAS unsigned char* lds, int tid, int bid, int G) {
;     ...
;             for (int kt = 0; kt < nt; kt += 2) {
;                 if (kt + 2 < nt) { const unsigned short* p = src + (size_t)(kt + 2) * 64 * 128; a0 = *(const u32x4*)p; a1 = *(const u32x4*)(p + 32 * 128); }
;                 indexer_tile(buf0, af, wv, sc0, sc1, kt, r32, h2);
;                 if (kt + 1 < nt) { *(LAS u32x4*)(buf1 + key0 * KT_ROWB + ch * 16) = b0; *(LAS u32x4*)(buf1 + (key0 + 32) * KT_ROWB + ch * 16) = b1; }
;                 __syncthreads();
;                 if (kt + 1 >= nt) break;
;                 if (kt + 3 < nt) { const unsigned short* p = src + (size_t)(kt + 3) * 64 * 128; b0 = *(const u32x4*)p; b1 = *(const u32x4*)(p + 32 * 128); }
;                 indexer_tile(buf1, af, wv, sc0, sc1, kt + 1, r32, h2);
	v_mfma_f32_32x32x16_f16 v[16:31], v[36:39], v[176:179], 0
	v_mfma_f32_32x32x16_f16 v[16:31], v[40:43], v[172:175], v[16:31]
	v_mfma_f32_32x32x16_f16 v[16:31], v[44:47], v[168:171], v[16:31]
	s_nop 8
	v_max_i32_e32 v0, 0, v0
	v_max_i32_e32 v1, 0, v1
	v_fma_f32 v243, v0, v116, 0
	v_fma_f32 v244, v1, v117, 0
	v_max_i32_e32 v2, 0, v2
	v_max_i32_e32 v3, 0, v3
	v_fma_f32 v243, v2, v118, v243
	v_mfma_f32_32x32x16_f16 v[16:31], v[48:51], v[164:167], v[16:31]
	v_fma_f32 v244, v3, v119, v244
	v_max_i32_e32 v4, 0, v4
	v_max_i32_e32 v5, 0, v5
	v_fma_f32 v243, v4, v120, v243
	v_fma_f32 v244, v5, v121, v244
	v_max_i32_e32 v6, 0, v6
	v_max_i32_e32 v7, 0, v7
	v_mfma_f32_32x32x16_f16 v[16:31], v[52:55], v[160:163], v[16:31]
	v_fma_f32 v243, v6, v122, v243
	v_fma_f32 v244, v7, v123, v244
	v_max_i32_e32 v8, 0, v8
	v_max_i32_e32 v9, 0, v9
	v_fma_f32 v243, v8, v124, v243
	v_fma_f32 v244, v9, v125, v244
	v_mfma_f32_32x32x16_f16 v[16:31], v[56:59], v[156:159], v[16:31]
	v_max_i32_e32 v10, 0, v10
	v_max_i32_e32 v11, 0, v11
	v_fma_f32 v243, v10, v126, v243
	v_fma_f32 v244, v11, v127, v244
	v_max_i32_e32 v12, 0, v12
	v_max_i32_e32 v13, 0, v13
	v_mfma_f32_32x32x16_f16 v[16:31], v[60:63], v[152:155], v[16:31]
	v_fma_f32 v243, v12, v128, v243
	v_fma_f32 v244, v13, v129, v244
	v_max_i32_e32 v14, 0, v14
	v_max_i32_e32 v15, 0, v15
	v_fma_f32 v243, v14, v130, v243
	v_fma_f32 v244, v15, v131, v244
	v_mfma_f32_32x32x16_f16 v[16:31], v[64:67], v[148:151], v[16:31]
	v_add_f32_e32 v245, v243, v244
	v_mov_b32_e32 v246, v245
	v_lshlrev_b32_e32 v247, 2, v32
	s_nop 0
	v_permlane32_swap_b32_e32 v246, v245
	v_add_f32_e32 v246, v246, v245
	s_mov_b64 exec, s[4:5]
	global_store_dword v247, v246, s[20:21]
	s_mov_b64 exec, -1
	v_mfma_f32_32x32x16_f16 v[0:15], v[84:87], v[176:179], 0
	v_mfma_f32_32x32x16_f16 v[0:15], v[88:91], v[172:175], v[0:15]
	v_mfma_f32_32x32x16_f16 v[0:15], v[92:95], v[168:171], v[0:15]
	s_nop 8
	v_max_i32_e32 v16, 0, v16
	v_max_i32_e32 v17, 0, v17
	v_fma_f32 v238, v16, v68, 0
	v_fma_f32 v239, v17, v69, 0
	v_max_i32_e32 v18, 0, v18
	v_max_i32_e32 v19, 0, v19
	v_fma_f32 v238, v18, v70, v238
	v_mfma_f32_32x32x16_f16 v[0:15], v[96:99], v[164:167], v[0:15]
	v_fma_f32 v239, v19, v71, v239
	v_max_i32_e32 v20, 0, v20
	v_max_i32_e32 v21, 0, v21
	v_fma_f32 v238, v20, v72, v238
	v_fma_f32 v239, v21, v73, v239
	v_max_i32_e32 v22, 0, v22
	v_max_i32_e32 v23, 0, v23
	v_mfma_f32_32x32x16_f16 v[0:15], v[100:103], v[160:163], v[0:15]
	v_fma_f32 v238, v22, v74, v238
	v_fma_f32 v239, v23, v75, v239
	v_max_i32_e32 v24, 0, v24
	v_max_i32_e32 v25, 0, v25
	v_fma_f32 v238, v24, v76, v238
	v_fma_f32 v239, v25, v77, v239
	v_mfma_f32_32x32x16_f16 v[0:15], v[104:107], v[156:159], v[0:15]
	v_max_i32_e32 v26, 0, v26
	v_max_i32_e32 v27, 0, v27
	v_fma_f32 v238, v26, v78, v238
	v_fma_f32 v239, v27, v79, v239
	v_max_i32_e32 v28, 0, v28
	v_max_i32_e32 v29, 0, v29
	v_mfma_f32_32x32x16_f16 v[0:15], v[108:111], v[152:155], v[0:15]
	v_fma_f32 v238, v28, v80, v238
	v_fma_f32 v239, v29, v81, v239
	v_max_i32_e32 v30, 0, v30
	v_max_i32_e32 v31, 0, v31
	v_fma_f32 v238, v30, v82, v238
	v_fma_f32 v239, v31, v83, v239
	v_mfma_f32_32x32x16_f16 v[0:15], v[112:115], v[148:151], v[0:15]
	v_add_f32_e32 v240, v238, v239
	v_mov_b32_e32 v241, v240
	v_lshlrev_b32_e32 v242, 2, v32
	s_nop 0
	v_permlane32_swap_b32_e32 v241, v240
	v_add_f32_e32 v241, v241, v240
	s_mov_b64 exec, s[4:5]
	global_store_dword v242, v241, s[18:19] offset:128
	s_mov_b64 exec, -1
	s_mov_b32 s98, 1
	s_add_i32 s27, s11, -3
	s_cmp_lt_i32 s27, s41
	s_cselect_b64 s[24:25], -1, 0
	s_cmp_ge_i32 s27, s41
	s_cbranch_scc1 .LBB0_1833
	s_waitcnt vmcnt(8)
	ds_write_b128 v209, v[140:143] offset:17408
	ds_write_b128 v209, v[144:147] offset:26112
.LBB0_1833:
	s_andn2_b64 vcc, exec, s[24:25]
	s_waitcnt lgkmcnt(0)
	s_barrier
	s_cbranch_vccnz .LBB0_1842
	s_cmp_gt_i32 s11, s41
	s_cbranch_scc1 .LBB0_1836
	v_add_co_u32_e32 v238, vcc, 0xffffe000, v34
	s_nop 1
	v_addc_co_u32_e32 v239, vcc, -1, v35, vcc
	global_load_dwordx4 v[140:143], v[238:239], off
	global_load_dwordx4 v[144:147], v[34:35], off
.LBB0_1836:
	ds_read_b128 v[250:253], v207 offset:17408
	ds_read_b128 v[210:213], v207 offset:17440
	ds_read_b128 v[214:217], v207 offset:17472
	ds_read_b128 v[218:221], v207 offset:17504
	ds_read_b128 v[222:225], v207 offset:17536
	ds_read_b128 v[226:229], v207 offset:17568
	ds_read_b128 v[230:233], v207 offset:17600
	ds_read_b128 v[234:237], v207 offset:17632
	ds_read_b128 v[176:179], v207 offset:26112
	ds_read_b128 v[172:175], v207 offset:26144
	ds_read_b128 v[168:171], v207 offset:26176
	ds_read_b128 v[164:167], v207 offset:26208
	ds_read_b128 v[160:163], v207 offset:26240
	ds_read_b128 v[156:159], v207 offset:26272
	ds_read_b128 v[152:155], v207 offset:26304
	ds_read_b128 v[148:151], v207 offset:26336
	s_cmp_eq_u32 s98, 0
	s_cbranch_scc1 .Lp11_skip1
	v_max_i32_e32 v0, 0, v0
	v_max_i32_e32 v1, 0, v1
	v_fma_f32 v243, v0, v116, 0
	v_fma_f32 v244, v1, v117, 0
	v_max_i32_e32 v2, 0, v2
	v_max_i32_e32 v3, 0, v3
	v_fma_f32 v243, v2, v118, v243
	v_fma_f32 v244, v3, v119, v244
	v_max_i32_e32 v4, 0, v4
	v_max_i32_e32 v5, 0, v5
	v_fma_f32 v243, v4, v120, v243
	v_fma_f32 v244, v5, v121, v244
	v_max_i32_e32 v6, 0, v6
	v_max_i32_e32 v7, 0, v7
	v_fma_f32 v243, v6, v122, v243
	v_fma_f32 v244, v7, v123, v244
	v_max_i32_e32 v8, 0, v8
	v_max_i32_e32 v9, 0, v9
	v_fma_f32 v243, v8, v124, v243
	v_fma_f32 v244, v9, v125, v244
	v_max_i32_e32 v10, 0, v10
	v_max_i32_e32 v11, 0, v11
	v_fma_f32 v243, v10, v126, v243
	v_fma_f32 v244, v11, v127, v244
	v_max_i32_e32 v12, 0, v12
	v_max_i32_e32 v13, 0, v13
	v_fma_f32 v243, v12, v128, v243
	v_fma_f32 v244, v13, v129, v244
	v_max_i32_e32 v14, 0, v14
	v_max_i32_e32 v15, 0, v15
	v_fma_f32 v243, v14, v130, v243
	v_fma_f32 v244, v15, v131, v244
	v_add_f32_e32 v245, v243, v244
	v_mov_b32_e32 v246, v245
	v_lshlrev_b32_e32 v247, 2, v32
	s_nop 0
	v_permlane32_swap_b32_e32 v246, v245
	v_add_f32_e32 v246, v246, v245
	s_mov_b64 exec, s[4:5]
	global_store_dword v247, v246, s[20:21] offset:128
	s_mov_b64 exec, -1
; #define LAS __attribute__((address_space(3)))
; DI void indexer_tile(const LAS unsigned char* buf, const f16x8 (&af)[2][8], const f32x4 (&wv)[2][4], float* sc0, float* sc1, int kt, int r32, int h2) {
;     ...
;         f32x2_t a0 = {0.f, 0.f}, a1 = {0.f, 0.f};
; #pragma unroll
;         for (int q = 0; q < 4; ++q)
; #pragma unroll
;             for (int e = 0; e < 4; e += 2) {
;                 const f32x2_t r0 = {relu1(c0[4 * q + e]), relu1(c0[4 * q + e + 1])};
;                 const f32x2_t r1 = {relu1(c1[4 * q + e]), relu1(c1[4 * q + e + 1])};
;                 const f32x2_t w0 = {wv[0][q][e], wv[0][q][e + 1]}, w1 = {wv[1][q][e], wv[1][q][e + 1]};
;                 a0 = __builtin_elementwise_fma(r0, w0, a0); a1 = __builtin_elementwise_fma(r1, w1, a1); }
;         float s0 = a0.x + a0.y, s1 = a1.x + a1.y;
;         s0 += __shfl_xor(s0, 32); s1 += __shfl_xor(s1, 32);
;         if (h2 == 0) { sc0[kt * 64 + 32 * sub + r32] = s0; sc1[kt * 64 + 32 * sub + r32] = s1; }
; DI void indexer_phase(const unsigned short* QI, const unsigned short* KI16, const float* WI, float* SC, LAS unsigned char* lds, int tid, int bid, int G) {
;     ...
;                 indexer_tile(buf0, af, wv, sc0, sc1, kt, r32, h2);
;                 if (kt + 1 < nt) { *(LAS u32x4*)(buf1 + key0 * KT_ROWB + ch * 16) = b0; *(LAS u32x4*)(buf1 + (key0 + 32) * KT_ROWB + ch * 16) = b1; }
;                 __syncthreads();
;                 if (kt + 1 >= nt) break;
;                 if (kt + 3 < nt) { const unsigned short* p = src + (size_t)(kt + 3) * 64 * 128; b0 = *(const u32x4*)p; b1 = *(const u32x4*)(p + 32 * 128); }
;                 indexer_tile(buf1, af, wv, sc0, sc1, kt + 1, r32, h2);
;                 if (kt + 2 < nt) { *(LAS u32x4*)(buf0 + key0 * KT_ROWB + ch * 16) = a0; *(LAS u32x4*)(buf0 + (key0 + 32) * KT_ROWB + ch * 16) = a1; }
;                 __syncthreads();
;             }
.Lp11_skip1:
	s_waitcnt lgkmcnt(15)
	v_mfma_f32_32x32x16_f16 v[16:31], v[36:39], v[250:253], 0
	s_waitcnt lgkmcnt(14)
	v_mfma_f32_32x32x16_f16 v[16:31], v[40:43], v[210:213], v[16:31]
	s_waitcnt lgkmcnt(13)
	v_mfma_f32_32x32x16_f16 v[16:31], v[44:47], v[214:217], v[16:31]
	s_waitcnt lgkmcnt(12)
	v_mfma_f32_32x32x16_f16 v[16:31], v[48:51], v[218:221], v[16:31]
	s_waitcnt lgkmcnt(11)
	v_mfma_f32_32x32x16_f16 v[16:31], v[52:55], v[222:225], v[16:31]
	s_waitcnt lgkmcnt(10)
	v_mfma_f32_32x32x16_f16 v[16:31], v[56:59], v[226:229], v[16:31]
	s_waitcnt lgkmcnt(9)
	v_mfma_f32_32x32x16_f16 v[16:31], v[60:63], v[230:233], v[16:31]
	s_waitcnt lgkmcnt(8)
	v_mfma_f32_32x32x16_f16 v[16:31], v[64:67], v[234:237], v[16:31]
	v_mfma_f32_32x32x16_f16 v[0:15], v[84:87], v[250:253], 0
	v_mfma_f32_32x32x16_f16 v[0:15], v[88:91], v[210:213], v[0:15]
	v_mfma_f32_32x32x16_f16 v[0:15], v[92:95], v[214:217], v[0:15]
	s_nop 8
	v_max_i32_e32 v16, 0, v16
	v_max_i32_e32 v17, 0, v17
	v_fma_f32 v238, v16, v68, 0
	v_fma_f32 v239, v17, v69, 0
	v_max_i32_e32 v18, 0, v18
	v_max_i32_e32 v19, 0, v19
	v_fma_f32 v238, v18, v70, v238
	v_mfma_f32_32x32x16_f16 v[0:15], v[96:99], v[218:221], v[0:15]
	v_fma_f32 v239, v19, v71, v239
	v_max_i32_e32 v20, 0, v20
	v_max_i32_e32 v21, 0, v21
	v_fma_f32 v238, v20, v72, v238
	v_fma_f32 v239, v21, v73, v239
	v_max_i32_e32 v22, 0, v22
	v_max_i32_e32 v23, 0, v23
	v_mfma_f32_32x32x16_f16 v[0:15], v[100:103], v[222:225], v[0:15]
	v_fma_f32 v238, v22, v74, v238
	v_fma_f32 v239, v23, v75, v239
	v_max_i32_e32 v24, 0, v24
	v_max_i32_e32 v25, 0, v25
	v_fma_f32 v238, v24, v76, v238
	v_fma_f32 v239, v25, v77, v239
	v_mfma_f32_32x32x16_f16 v[0:15], v[104:107], v[226:229], v[0:15]
	v_max_i32_e32 v26, 0, v26
	v_max_i32_e32 v27, 0, v27
	v_fma_f32 v238, v26, v78, v238
	v_fma_f32 v239, v27, v79, v239
	v_max_i32_e32 v28, 0, v28
	v_max_i32_e32 v29, 0, v29
	v_mfma_f32_32x32x16_f16 v[0:15], v[108:111], v[230:233], v[0:15]
	v_fma_f32 v238, v28, v80, v238
	v_fma_f32 v239, v29, v81, v239
	v_max_i32_e32 v30, 0, v30
	v_max_i32_e32 v31, 0, v31
	v_fma_f32 v238, v30, v82, v238
	v_fma_f32 v239, v31, v83, v239
	v_mfma_f32_32x32x16_f16 v[0:15], v[112:115], v[234:237], v[0:15]
	v_add_f32_e32 v240, v238, v239
	v_mov_b32_e32 v241, v240
	v_lshlrev_b32_e32 v242, 2, v32
	s_nop 0
	v_permlane32_swap_b32_e32 v241, v240
	v_add_f32_e32 v241, v241, v240
	s_mov_b64 exec, s[4:5]
	global_store_dword v242, v241, s[18:19] offset:256
	s_mov_b64 exec, -1
	s_waitcnt lgkmcnt(0)
	v_mfma_f32_32x32x16_f16 v[16:31], v[36:39], v[176:179], 0
	v_mfma_f32_32x32x16_f16 v[16:31], v[40:43], v[172:175], v[16:31]
	v_mfma_f32_32x32x16_f16 v[16:31], v[44:47], v[168:171], v[16:31]
	s_nop 8
	v_max_i32_e32 v0, 0, v0
	v_max_i32_e32 v1, 0, v1
	v_fma_f32 v243, v0, v116, 0
	v_fma_f32 v244, v1, v117, 0
	v_max_i32_e32 v2, 0, v2
	v_max_i32_e32 v3, 0, v3
	v_fma_f32 v243, v2, v118, v243
	v_mfma_f32_32x32x16_f16 v[16:31], v[48:51], v[164:167], v[16:31]
	v_fma_f32 v244, v3, v119, v244
	v_max_i32_e32 v4, 0, v4
	v_max_i32_e32 v5, 0, v5
	v_fma_f32 v243, v4, v120, v243
	v_fma_f32 v244, v5, v121, v244
	v_max_i32_e32 v6, 0, v6
	v_max_i32_e32 v7, 0, v7
	v_mfma_f32_32x32x16_f16 v[16:31], v[52:55], v[160:163], v[16:31]
	v_fma_f32 v243, v6, v122, v243
	v_fma_f32 v244, v7, v123, v244
	v_max_i32_e32 v8, 0, v8
	v_max_i32_e32 v9, 0, v9
	v_fma_f32 v243, v8, v124, v243
	v_fma_f32 v244, v9, v125, v244
	v_mfma_f32_32x32x16_f16 v[16:31], v[56:59], v[156:159], v[16:31]
	v_max_i32_e32 v10, 0, v10
	v_max_i32_e32 v11, 0, v11
	v_fma_f32 v243, v10, v126, v243
	v_fma_f32 v244, v11, v127, v244
	v_max_i32_e32 v12, 0, v12
	v_max_i32_e32 v13, 0, v13
	v_mfma_f32_32x32x16_f16 v[16:31], v[60:63], v[152:155], v[16:31]
	v_fma_f32 v243, v12, v128, v243
	v_fma_f32 v244, v13, v129, v244
	v_max_i32_e32 v14, 0, v14
	v_max_i32_e32 v15, 0, v15
	v_fma_f32 v243, v14, v130, v243
	v_fma_f32 v244, v15, v131, v244
	v_mfma_f32_32x32x16_f16 v[16:31], v[64:67], v[148:151], v[16:31]
	v_add_f32_e32 v245, v243, v244
	v_mov_b32_e32 v246, v245
	v_lshlrev_b32_e32 v247, 2, v32
	s_nop 0
	v_permlane32_swap_b32_e32 v246, v245
	v_add_f32_e32 v246, v246, v245
	s_mov_b64 exec, s[4:5]
	global_store_dword v247, v246, s[20:21] offset:256
	s_mov_b64 exec, -1
	v_mfma_f32_32x32x16_f16 v[0:15], v[84:87], v[176:179], 0
	v_mfma_f32_32x32x16_f16 v[0:15], v[88:91], v[172:175], v[0:15]
	v_mfma_f32_32x32x16_f16 v[0:15], v[92:95], v[168:171], v[0:15]
	s_nop 8
	v_max_i32_e32 v16, 0, v16
	v_max_i32_e32 v17, 0, v17
	v_fma_f32 v238, v16, v68, 0
	v_fma_f32 v239, v17, v69, 0
	v_max_i32_e32 v18, 0, v18
	v_max_i32_e32 v19, 0, v19
	v_fma_f32 v238, v18, v70, v238
	v_mfma_f32_32x32x16_f16 v[0:15], v[96:99], v[164:167], v[0:15]
	v_fma_f32 v239, v19, v71, v239
	v_max_i32_e32 v20, 0, v20
	v_max_i32_e32 v21, 0, v21
	v_fma_f32 v238, v20, v72, v238
	v_fma_f32 v239, v21, v73, v239
	v_max_i32_e32 v22, 0, v22
	v_max_i32_e32 v23, 0, v23
	v_mfma_f32_32x32x16_f16 v[0:15], v[100:103], v[160:163], v[0:15]
	v_fma_f32 v238, v22, v74, v238
	v_fma_f32 v239, v23, v75, v239
	v_max_i32_e32 v24, 0, v24
	v_max_i32_e32 v25, 0, v25
	v_fma_f32 v238, v24, v76, v238
	v_fma_f32 v239, v25, v77, v239
	v_mfma_f32_32x32x16_f16 v[0:15], v[104:107], v[156:159], v[0:15]
	v_max_i32_e32 v26, 0, v26
	v_max_i32_e32 v27, 0, v27
	v_fma_f32 v238, v26, v78, v238
	v_fma_f32 v239, v27, v79, v239
	v_max_i32_e32 v28, 0, v28
	v_max_i32_e32 v29, 0, v29
	v_mfma_f32_32x32x16_f16 v[0:15], v[108:111], v[152:155], v[0:15]
	v_fma_f32 v238, v28, v80, v238
	v_fma_f32 v239, v29, v81, v239
	v_max_i32_e32 v30, 0, v30
	v_max_i32_e32 v31, 0, v31
	v_fma_f32 v238, v30, v82, v238
	v_fma_f32 v239, v31, v83, v239
	v_mfma_f32_32x32x16_f16 v[0:15], v[112:115], v[148:151], v[0:15]
	v_add_f32_e32 v240, v238, v239
	v_mov_b32_e32 v241, v240
	v_lshlrev_b32_e32 v242, 2, v32
	s_nop 0
	v_permlane32_swap_b32_e32 v241, v240
	v_add_f32_e32 v241, v241, v240
	s_mov_b64 exec, s[4:5]
	global_store_dword v242, v241, s[18:19] offset:384
	s_mov_b64 exec, -1
	s_mov_b32 s98, 1
	s_andn2_b64 vcc, exec, s[22:23]
	s_cbranch_vccnz .LBB0_1824
	s_waitcnt vmcnt(7)
	ds_write_b128 v209, v[132:135]
	ds_write_b128 v209, v[136:139] offset:8704
	s_branch .LBB0_1824
; DI void indexer_tile(const LAS unsigned char* buf, const f16x8 (&af)[2][8], const f32x4 (&wv)[2][4], float* sc0, float* sc1, int kt, int r32, int h2) {
;     ...
;         f32x2_t a0 = {0.f, 0.f}, a1 = {0.f, 0.f};
; #pragma unroll
;         for (int q = 0; q < 4; ++q)
; #pragma unroll
;             for (int e = 0; e < 4; e += 2) {
;                 const f32x2_t r0 = {relu1(c0[4 * q + e]), relu1(c0[4 * q + e + 1])};
;                 const f32x2_t r1 = {relu1(c1[4 * q + e]), relu1(c1[4 * q + e + 1])};
;                 const f32x2_t w0 = {wv[0][q][e], wv[0][q][e + 1]}, w1 = {wv[1][q][e], wv[1][q][e + 1]};
;                 a0 = __builtin_elementwise_fma(r0, w0, a0); a1 = __builtin_elementwise_fma(r1, w1, a1); }
;         float s0 = a0.x + a0.y, s1 = a1.x + a1.y;
;         s0 += __shfl_xor(s0, 32); s1 += __shfl_xor(s1, 32);
;         if (h2 == 0) { sc0[kt * 64 + 32 * sub + r32] = s0; sc1[kt * 64 + 32 * sub + r32] = s1; }
; DI void indexer_phase(const unsigned short* QI, const unsigned short* KI16, const float* WI, float* SC, LAS unsigned char* lds, int tid, int bid, int G) {
;     ...
;         for (int it = 0; it < 4; ++it) {
;             const int b = it >> 1, gi = (it & 1) ? (511 - v) : v; const int tb = 16 * gi;
;             const int nt = ((tb + 15) >> 6) + 1;
;             f16x8 af[2][8]; f32x4 wv[2][4];
; #pragma unroll
;             for (int tq = 0; tq < 2; ++tq) { const size_t tg = (size_t)b * SEQ + tb + 2 * w + tq;
; #pragma unroll
;                 for (int ks = 0; ks < 8; ++ks) af[tq][ks] = *(const f16x8*)(QI + tg * 4096 + r32 * 128 + 16 * ks + 8 * h2);
; #pragma unroll
;                 for (int q = 0; q < 4; ++q) wv[tq][q] = *(const f32x4*)(WI + tg * 32 + 8 * q + 4 * h2); }
;             float* sc0 = SC + sc_row_off(b, tb + 2 * w); float* sc1 = SC + sc_row_off(b, tb + 2 * w + 1);
;             const unsigned short* src = KI16 + (size_t)b * SEQ * 128 + (size_t)key0 * 128 + ch * 8;
;             u32x4 a0, a1, b0 = {0u, 0u, 0u, 0u}, b1 = {0u, 0u, 0u, 0u};
;             a0 = *(const u32x4*)src; a1 = *(const u32x4*)(src + 32 * 128);
;             if (nt > 1) { b0 = *(const u32x4*)(src + 64 * 128); b1 = *(const u32x4*)(src + 96 * 128); }
;             __syncthreads();
;             *(LAS u32x4*)(buf0 + key0 * KT_ROWB + ch * 16) = a0; *(LAS u32x4*)(buf0 + (key0 + 32) * KT_ROWB + ch * 16) = a1;
;             __syncthreads();
.LBB0_1842:
	v_max_i32_e32 v0, 0, v0
	v_max_i32_e32 v1, 0, v1
	v_fma_f32 v243, v0, v116, 0
	v_fma_f32 v244, v1, v117, 0
	v_max_i32_e32 v2, 0, v2
	v_max_i32_e32 v3, 0, v3
	v_fma_f32 v243, v2, v118, v243
	v_fma_f32 v244, v3, v119, v244
	v_max_i32_e32 v4, 0, v4
	v_max_i32_e32 v5, 0, v5
	v_fma_f32 v243, v4, v120, v243
	v_fma_f32 v244, v5, v121, v244
	v_max_i32_e32 v6, 0, v6
	v_max_i32_e32 v7, 0, v7
	v_fma_f32 v243, v6, v122, v243
	v_fma_f32 v244, v7, v123, v244
	v_max_i32_e32 v8, 0, v8
	v_max_i32_e32 v9, 0, v9
	v_fma_f32 v243, v8, v124, v243
	v_fma_f32 v244, v9, v125, v244
	v_max_i32_e32 v10, 0, v10
	v_max_i32_e32 v11, 0, v11
	v_fma_f32 v243, v10, v126, v243
	v_fma_f32 v244, v11, v127, v244
	v_max_i32_e32 v12, 0, v12
	v_max_i32_e32 v13, 0, v13
	v_fma_f32 v243, v12, v128, v243
	v_fma_f32 v244, v13, v129, v244
	v_max_i32_e32 v14, 0, v14
	v_max_i32_e32 v15, 0, v15
	v_fma_f32 v243, v14, v130, v243
	v_fma_f32 v244, v15, v131, v244
	v_add_f32_e32 v245, v243, v244
	v_mov_b32_e32 v246, v245
	v_lshlrev_b32_e32 v247, 2, v32
	s_nop 0
	v_permlane32_swap_b32_e32 v246, v245
	v_add_f32_e32 v246, v246, v245
	s_mov_b64 exec, s[4:5]
	global_store_dword v247, v246, s[20:21] offset:128
	s_mov_b64 exec, -1
	s_mov_b32 s98, 0
	s_cbranch_execz .LBB0_1825
.LBB0_1843:
	s_sub_i32 s11, 0x1ff, s40
	s_lshl_b32 s45, s11, 4
	s_add_u32 s18, s45, s36
	s_addc_u32 s19, 0, s37
	s_lshl_b64 s[20:21], s[18:19], 13
	v_lshl_add_u64 v[0:1], v[180:181], 0, s[20:21]
	s_lshl_b64 s[20:21], s[18:19], 7
	s_or_b32 s18, s18, 1
	global_load_dwordx4 v[34:37], v[0:1], off
	global_load_dwordx4 v[38:41], v[0:1], off offset:32
	global_load_dwordx4 v[42:45], v[0:1], off offset:64
	global_load_dwordx4 v[46:49], v[0:1], off offset:96
	global_load_dwordx4 v[50:53], v[0:1], off offset:128
	global_load_dwordx4 v[54:57], v[0:1], off offset:160
	global_load_dwordx4 v[58:61], v[0:1], off offset:192
	global_load_dwordx4 v[62:65], v[0:1], off offset:224
	v_lshl_add_u64 v[0:1], v[182:183], 0, s[20:21]
	s_lshl_b64 s[20:21], s[18:19], 13
	global_load_dwordx4 v[66:69], v[0:1], off
	global_load_dwordx4 v[70:73], v[0:1], off offset:32
	global_load_dwordx4 v[74:77], v[0:1], off offset:64
	global_load_dwordx4 v[78:81], v[0:1], off offset:96
	v_lshl_add_u64 v[0:1], v[180:181], 0, s[20:21]
	global_load_dwordx4 v[82:85], v[0:1], off
	global_load_dwordx4 v[86:89], v[0:1], off offset:32
	global_load_dwordx4 v[90:93], v[0:1], off offset:64
	global_load_dwordx4 v[94:97], v[0:1], off offset:96
	global_load_dwordx4 v[98:101], v[0:1], off offset:128
	global_load_dwordx4 v[102:105], v[0:1], off offset:160
	global_load_dwordx4 v[106:109], v[0:1], off offset:192
	global_load_dwordx4 v[110:113], v[0:1], off offset:224
	s_lshl_b64 s[18:19], s[18:19], 7
	v_lshl_add_u64 v[0:1], v[182:183], 0, s[18:19]
	global_load_dwordx4 v[130:133], v[184:185], off
	global_load_dwordx4 v[138:141], v[186:187], off
	global_load_dwordx4 v[114:117], v[0:1], off
	global_load_dwordx4 v[118:121], v[0:1], off offset:32
	global_load_dwordx4 v[134:137], v[190:191], off
	global_load_dwordx4 v[142:145], v[188:189], off
	global_load_dwordx4 v[122:125], v[0:1], off offset:64
	global_load_dwordx4 v[126:129], v[0:1], off offset:96
	s_lshr_b32 s42, s11, 2
	s_add_i32 s11, s45, s36
	s_ashr_i32 s18, s11, 7
	s_add_i32 s19, s18, 1
	s_mul_i32 s18, s19, s18
	s_ashr_i32 s18, s18, 1
	s_lshl_b32 s26, s19, 7
	s_ashr_i32 s19, s18, 31
	s_and_b32 s11, s11, 0x7e
	s_lshl_b64 s[22:23], s[18:19], 16
	s_mul_hi_i32 s21, s26, s11
	s_mul_i32 s20, s26, s11
	s_add_u32 s27, s17, s22
	s_addc_u32 s28, s33, s23
	s_lshl_b64 s[20:21], s[20:21], 2
	s_add_u32 s24, s27, s20
	s_addc_u32 s25, s28, s21
	s_or_b32 s11, s11, 1
	s_mul_hi_i32 s23, s26, s11
	s_mul_i32 s22, s26, s11
	s_lshl_b64 s[22:23], s[22:23], 2
	s_add_u32 s26, s27, s22
	s_addc_u32 s27, s28, s23
	s_mov_b32 s11, 3
	v_mov_b32_e32 v32, v206
	v_mov_b64_e32 v[178:179], v[200:201]
	s_barrier
	s_waitcnt vmcnt(7)
	ds_write_b128 v209, v[130:133]
	s_waitcnt vmcnt(0)
	ds_write_b128 v209, v[138:141] offset:8704
	s_waitcnt lgkmcnt(0)
	s_barrier
	s_mov_b32 s98, 0
	s_branch .LBB0_1845
.Lp11_fb1:
	v_max_i32_e32 v0, 0, v0
	v_max_i32_e32 v1, 0, v1
	v_fma_f32 v243, v0, v114, 0
	v_fma_f32 v244, v1, v115, 0
	v_max_i32_e32 v2, 0, v2
	v_max_i32_e32 v3, 0, v3
	v_fma_f32 v243, v2, v116, v243
	v_fma_f32 v244, v3, v117, v244
	v_max_i32_e32 v4, 0, v4
	v_max_i32_e32 v5, 0, v5
	v_fma_f32 v243, v4, v118, v243
	v_fma_f32 v244, v5, v119, v244
	v_max_i32_e32 v6, 0, v6
	v_max_i32_e32 v7, 0, v7
	v_fma_f32 v243, v6, v120, v243
	v_fma_f32 v244, v7, v121, v244
	v_max_i32_e32 v8, 0, v8
	v_max_i32_e32 v9, 0, v9
	v_fma_f32 v243, v8, v122, v243
	v_fma_f32 v244, v9, v123, v244
	v_max_i32_e32 v10, 0, v10
	v_max_i32_e32 v11, 0, v11
	v_fma_f32 v243, v10, v124, v243
	v_fma_f32 v244, v11, v125, v244
	v_max_i32_e32 v12, 0, v12
	v_max_i32_e32 v13, 0, v13
	v_fma_f32 v243, v12, v126, v243
	v_fma_f32 v244, v13, v127, v244
	v_max_i32_e32 v14, 0, v14
	v_max_i32_e32 v15, 0, v15
	v_fma_f32 v243, v14, v128, v243
	v_fma_f32 v244, v15, v129, v244
	v_add_f32_e32 v245, v243, v244
	v_mov_b32_e32 v246, v245
	v_lshlrev_b32_e32 v247, 2, v32
	s_nop 0
	v_permlane32_swap_b32_e32 v246, v245
	v_add_f32_e32 v246, v246, v245
	s_mov_b64 exec, s[4:5]
	global_store_dword v247, v246, s[26:27] offset:-128
	s_mov_b64 exec, -1
	s_mov_b32 s98, 0
	s_branch .LBB0_1863

; #define LAS __attribute__((address_space(3)))
; DI void indexer_tile(const LAS unsigned char* buf, const f16x8 (&af)[2][8], const f32x4 (&wv)[2][4], float* sc0, float* sc1, int kt, int r32, int h2) {
;     ...
;     f16x8 bfr[2][8];
; #pragma unroll
;     for (int sub = 0; sub < 2; ++sub)
; #pragma unroll
;         for (int ks = 0; ks < 8; ++ks) bfr[sub][ks] = *(const LAS f16x8*)(buf + (32 * sub + r32) * KT_ROWB + (16 * ks + 8 * h2) * 2);
;     __builtin_amdgcn_sched_barrier(0);
; #pragma unroll
;     for (int sub = 0; sub < 2; ++sub) {
;         f32x16 c0, c1;
; #pragma unroll
;         for (int i = 0; i < 16; ++i) { c0[i] = 0.f; c1[i] = 0.f; }
; #pragma unroll
;         for (int ks = 0; ks < 8; ++ks) { c0 = __builtin_amdgcn_mfma_f32_32x32x16_f16(af[0][ks], bfr[sub][ks], c0, 0, 0, 0); c1 = __builtin_amdgcn_mfma_f32_32x32x16_f16(af[1][ks], bfr[sub][ks], c1, 0, 0, 0); }
;         f32x2_t a0 = {0.f, 0.f}, a1 = {0.f, 0.f};
; #pragma unroll
;         for (int q = 0; q < 4; ++q)
; #pragma unroll
;             for (int e = 0; e < 4; e += 2) {
;                 const f32x2_t r0 = {relu1(c0[4 * q + e]), relu1(c0[4 * q + e + 1])};
;                 const f32x2_t r1 = {relu1(c1[4 * q + e]), relu1(c1[4 * q + e + 1])};
;                 const f32x2_t w0 = {wv[0][q][e], wv[0][q][e + 1]}, w1 = {wv[1][q][e], wv[1][q][e + 1]};
;                 a0 = __builtin_elementwise_fma(r0, w0, a0); a1 = __builtin_elementwise_fma(r1, w1, a1); }
;         float s0 = a0.x + a0.y, s1 = a1.x + a1.y;
;         s0 += __shfl_xor(s0, 32); s1 += __shfl_xor(s1, 32);
;         if (h2 == 0) { sc0[kt * 64 + 32 * sub + r32] = s0; sc1[kt * 64 + 32 * sub + r32] = s1; }
; DI void indexer_phase(const unsigned short* QI, const unsigned short* KI16, const float* WI, float* SC, LAS unsigned char* lds, int tid, int bid, int G) {
;     ...
;             for (int kt = 0; kt < nt; kt += 2) {
;                 if (kt + 2 < nt) { const unsigned short* p = src + (size_t)(kt + 2) * 64 * 128; a0 = *(const u32x4*)p; a1 = *(const u32x4*)(p + 32 * 128); }
;                 indexer_tile(buf0, af, wv, sc0, sc1, kt, r32, h2);
.LBB0_1845:
	s_add_i32 s46, s11, -1
	s_cmp_le_u32 s46, s42
	s_cselect_b64 s[28:29], -1, 0
	s_cmp_gt_u32 s46, s42
	s_cbranch_scc1 .LBB0_1847
	v_add_co_u32_e32 v238, vcc, 0xffffa000, v178
	s_nop 1
	v_addc_co_u32_e32 v239, vcc, -1, v179, vcc
	v_add_co_u32_e32 v240, vcc, 0xffffc000, v178
	s_nop 1
	v_addc_co_u32_e32 v241, vcc, -1, v179, vcc
	global_load_dwordx4 v[130:133], v[238:239], off
	global_load_dwordx4 v[138:141], v[240:241], off
.LBB0_1847:
	ds_read_b128 v[250:253], v207
	ds_read_b128 v[210:213], v207 offset:32
	ds_read_b128 v[214:217], v207 offset:64
	ds_read_b128 v[218:221], v207 offset:96
	ds_read_b128 v[222:225], v207 offset:128
	ds_read_b128 v[226:229], v207 offset:160
	ds_read_b128 v[230:233], v207 offset:192
	ds_read_b128 v[234:237], v207 offset:224
	ds_read_b128 v[174:177], v207 offset:8704
	ds_read_b128 v[170:173], v207 offset:8736
	ds_read_b128 v[166:169], v207 offset:8768
	ds_read_b128 v[162:165], v207 offset:8800
	ds_read_b128 v[158:161], v207 offset:8832
	ds_read_b128 v[154:157], v207 offset:8864
	ds_read_b128 v[150:153], v207 offset:8896
	ds_read_b128 v[146:149], v207 offset:8928
	s_cmp_eq_u32 s98, 0
	s_cbranch_scc1 .Lp11_skip2
	v_max_i32_e32 v0, 0, v0
	v_max_i32_e32 v1, 0, v1
	v_fma_f32 v243, v0, v114, 0
	v_fma_f32 v244, v1, v115, 0
	v_max_i32_e32 v2, 0, v2
	v_max_i32_e32 v3, 0, v3
	v_fma_f32 v243, v2, v116, v243
	v_fma_f32 v244, v3, v117, v244
	v_max_i32_e32 v4, 0, v4
	v_max_i32_e32 v5, 0, v5
	v_fma_f32 v243, v4, v118, v243
	v_fma_f32 v244, v5, v119, v244
	v_max_i32_e32 v6, 0, v6
	v_max_i32_e32 v7, 0, v7
	v_fma_f32 v243, v6, v120, v243
	v_fma_f32 v244, v7, v121, v244
	v_max_i32_e32 v8, 0, v8
	v_max_i32_e32 v9, 0, v9
	v_fma_f32 v243, v8, v122, v243
	v_fma_f32 v244, v9, v123, v244
	v_max_i32_e32 v10, 0, v10
	v_max_i32_e32 v11, 0, v11
	v_fma_f32 v243, v10, v124, v243
	v_fma_f32 v244, v11, v125, v244
	v_max_i32_e32 v12, 0, v12
	v_max_i32_e32 v13, 0, v13
	v_fma_f32 v243, v12, v126, v243
	v_fma_f32 v244, v13, v127, v244
	v_max_i32_e32 v14, 0, v14
	v_max_i32_e32 v15, 0, v15
	v_fma_f32 v243, v14, v128, v243
	v_fma_f32 v244, v15, v129, v244
	v_add_f32_e32 v245, v243, v244
	v_mov_b32_e32 v246, v245
	v_lshlrev_b32_e32 v247, 2, v32
	s_nop 0
	v_permlane32_swap_b32_e32 v246, v245
	v_add_f32_e32 v246, v246, v245
	s_mov_b64 exec, s[4:5]
	global_store_dword v247, v246, s[26:27] offset:-128
	s_mov_b64 exec, -1
.Lp11_skip2:
	s_waitcnt lgkmcnt(15)
	v_mfma_f32_32x32x16_f16 v[16:31], v[34:37], v[250:253], 0
	s_waitcnt lgkmcnt(14)
	v_mfma_f32_32x32x16_f16 v[16:31], v[38:41], v[210:213], v[16:31]
	s_waitcnt lgkmcnt(13)
	v_mfma_f32_32x32x16_f16 v[16:31], v[42:45], v[214:217], v[16:31]
	s_waitcnt lgkmcnt(12)
	v_mfma_f32_32x32x16_f16 v[16:31], v[46:49], v[218:221], v[16:31]
	s_waitcnt lgkmcnt(11)
	v_mfma_f32_32x32x16_f16 v[16:31], v[50:53], v[222:225], v[16:31]
	s_waitcnt lgkmcnt(10)
	v_mfma_f32_32x32x16_f16 v[16:31], v[54:57], v[226:229], v[16:31]
	s_waitcnt lgkmcnt(9)
	v_mfma_f32_32x32x16_f16 v[16:31], v[58:61], v[230:233], v[16:31]
	s_waitcnt lgkmcnt(8)
	v_mfma_f32_32x32x16_f16 v[16:31], v[62:65], v[234:237], v[16:31]
	v_mfma_f32_32x32x16_f16 v[0:15], v[82:85], v[250:253], 0
	v_mfma_f32_32x32x16_f16 v[0:15], v[86:89], v[210:213], v[0:15]
	v_mfma_f32_32x32x16_f16 v[0:15], v[90:93], v[214:217], v[0:15]
	s_nop 8
	v_max_i32_e32 v16, 0, v16
	v_max_i32_e32 v17, 0, v17
	v_fma_f32 v238, v16, v66, 0
	v_fma_f32 v239, v17, v67, 0
	v_max_i32_e32 v18, 0, v18
	v_max_i32_e32 v19, 0, v19
	v_fma_f32 v238, v18, v68, v238
	v_mfma_f32_32x32x16_f16 v[0:15], v[94:97], v[218:221], v[0:15]
	v_fma_f32 v239, v19, v69, v239
	v_max_i32_e32 v20, 0, v20
	v_max_i32_e32 v21, 0, v21
	v_fma_f32 v238, v20, v70, v238
	v_fma_f32 v239, v21, v71, v239
	v_max_i32_e32 v22, 0, v22
	v_max_i32_e32 v23, 0, v23
	v_mfma_f32_32x32x16_f16 v[0:15], v[98:101], v[222:225], v[0:15]
	v_fma_f32 v238, v22, v72, v238
	v_fma_f32 v239, v23, v73, v239
	v_max_i32_e32 v24, 0, v24
	v_max_i32_e32 v25, 0, v25
	v_fma_f32 v238, v24, v74, v238
	v_fma_f32 v239, v25, v75, v239
	v_mfma_f32_32x32x16_f16 v[0:15], v[102:105], v[226:229], v[0:15]
	v_max_i32_e32 v26, 0, v26
	v_max_i32_e32 v27, 0, v27
	v_fma_f32 v238, v26, v76, v238
	v_fma_f32 v239, v27, v77, v239
	v_max_i32_e32 v28, 0, v28
	v_max_i32_e32 v29, 0, v29
	v_mfma_f32_32x32x16_f16 v[0:15], v[106:109], v[230:233], v[0:15]
	v_fma_f32 v238, v28, v78, v238
	v_fma_f32 v239, v29, v79, v239
	v_max_i32_e32 v30, 0, v30
	v_max_i32_e32 v31, 0, v31
	v_fma_f32 v238, v30, v80, v238
	v_fma_f32 v239, v31, v81, v239
	v_mfma_f32_32x32x16_f16 v[0:15], v[110:113], v[234:237], v[0:15]
	v_add_f32_e32 v240, v238, v239
	v_mov_b32_e32 v241, v240
	v_lshlrev_b32_e32 v242, 2, v32
	s_nop 0
	v_permlane32_swap_b32_e32 v241, v240
	v_add_f32_e32 v241, v241, v240
	s_mov_b64 exec, s[4:5]
	global_store_dword v242, v241, s[24:25]
	s_mov_b64 exec, -1
	s_waitcnt lgkmcnt(0)
; #define LAS __attribute__((address_space(3)))
; DI void indexer_tile(const LAS unsigned char* buf, const f16x8 (&af)[2][8], const f32x4 (&wv)[2][4], float* sc0, float* sc1, int kt, int r32, int h2) {
;     ...
;         f32x2_t a0 = {0.f, 0.f}, a1 = {0.f, 0.f};
; #pragma unroll
;         for (int q = 0; q < 4; ++q)
; #pragma unroll
;             for (int e = 0; e < 4; e += 2) {
;                 const f32x2_t r0 = {relu1(c0[4 * q + e]), relu1(c0[4 * q + e + 1])};
;                 const f32x2_t r1 = {relu1(c1[4 * q + e]), relu1(c1[4 * q + e + 1])};
;                 const f32x2_t w0 = {wv[0][q][e], wv[0][q][e + 1]}, w1 = {wv[1][q][e], wv[1][q][e + 1]};
;                 a0 = __builtin_elementwise_fma(r0, w0, a0); a1 = __builtin_elementwise_fma(r1, w1, a1); }
;         float s0 = a0.x + a0.y, s1 = a1.x + a1.y;
;         s0 += __shfl_xor(s0, 32); s1 += __shfl_xor(s1, 32);
;         if (h2 == 0) { sc0[kt * 64 + 32 * sub + r32] = s0; sc1[kt * 64 + 32 * sub + r32] = s1; }
; DI void indexer_phase(const unsigned short* QI, const unsigned short* KI16, const float* WI, float* SC, LAS unsigned char* lds, int tid, int bid, int G) {
;     ...
;             for (int kt = 0; kt < nt; kt += 2) {
;                 if (kt + 2 < nt) { const unsigned short* p = src + (size_t)(kt + 2) * 64 * 128; a0 = *(const u32x4*)p; a1 = *(const u32x4*)(p + 32 * 128); }
;                 indexer_tile(buf0, af, wv, sc0, sc1, kt, r32, h2);
;                 if (kt + 1 < nt) { *(LAS u32x4*)(buf1 + key0 * KT_ROWB + ch * 16) = b0; *(LAS u32x4*)(buf1 + (key0 + 32) * KT_ROWB + ch * 16) = b1; }
;                 __syncthreads();
;                 if (kt + 1 >= nt) break;
;                 if (kt + 3 < nt) { const unsigned short* p = src + (size_t)(kt + 3) * 64 * 128; b0 = *(const u32x4*)p; b1 = *(const u32x4*)(p + 32 * 128); }
;                 indexer_tile(buf1, af, wv, sc0, sc1, kt + 1, r32, h2);
	v_mfma_f32_32x32x16_f16 v[16:31], v[34:37], v[174:177], 0
	v_mfma_f32_32x32x16_f16 v[16:31], v[38:41], v[170:173], v[16:31]
	v_mfma_f32_32x32x16_f16 v[16:31], v[42:45], v[166:169], v[16:31]
	s_nop 8
	v_max_i32_e32 v0, 0, v0
	v_max_i32_e32 v1, 0, v1
	v_fma_f32 v243, v0, v114, 0
	v_fma_f32 v244, v1, v115, 0
	v_max_i32_e32 v2, 0, v2
	v_max_i32_e32 v3, 0, v3
	v_fma_f32 v243, v2, v116, v243
	v_mfma_f32_32x32x16_f16 v[16:31], v[46:49], v[162:165], v[16:31]
	v_fma_f32 v244, v3, v117, v244
	v_max_i32_e32 v4, 0, v4
	v_max_i32_e32 v5, 0, v5
	v_fma_f32 v243, v4, v118, v243
	v_fma_f32 v244, v5, v119, v244
	v_max_i32_e32 v6, 0, v6
	v_max_i32_e32 v7, 0, v7
	v_mfma_f32_32x32x16_f16 v[16:31], v[50:53], v[158:161], v[16:31]
	v_fma_f32 v243, v6, v120, v243
	v_fma_f32 v244, v7, v121, v244
	v_max_i32_e32 v8, 0, v8
	v_max_i32_e32 v9, 0, v9
	v_fma_f32 v243, v8, v122, v243
	v_fma_f32 v244, v9, v123, v244
	v_mfma_f32_32x32x16_f16 v[16:31], v[54:57], v[154:157], v[16:31]
	v_max_i32_e32 v10, 0, v10
	v_max_i32_e32 v11, 0, v11
	v_fma_f32 v243, v10, v124, v243
	v_fma_f32 v244, v11, v125, v244
	v_max_i32_e32 v12, 0, v12
	v_max_i32_e32 v13, 0, v13
	v_mfma_f32_32x32x16_f16 v[16:31], v[58:61], v[150:153], v[16:31]
	v_fma_f32 v243, v12, v126, v243
	v_fma_f32 v244, v13, v127, v244
	v_max_i32_e32 v14, 0, v14
	v_max_i32_e32 v15, 0, v15
	v_fma_f32 v243, v14, v128, v243
	v_fma_f32 v244, v15, v129, v244
	v_mfma_f32_32x32x16_f16 v[16:31], v[62:65], v[146:149], v[16:31]
	v_add_f32_e32 v245, v243, v244
	v_mov_b32_e32 v246, v245
	v_lshlrev_b32_e32 v247, 2, v32
	s_nop 0
	v_permlane32_swap_b32_e32 v246, v245
	v_add_f32_e32 v246, v246, v245
	s_mov_b64 exec, s[4:5]
	global_store_dword v247, v246, s[26:27]
	s_mov_b64 exec, -1
	v_mfma_f32_32x32x16_f16 v[0:15], v[82:85], v[174:177], 0
	v_mfma_f32_32x32x16_f16 v[0:15], v[86:89], v[170:173], v[0:15]
	v_mfma_f32_32x32x16_f16 v[0:15], v[90:93], v[166:169], v[0:15]
	s_nop 8
	v_max_i32_e32 v16, 0, v16
	v_max_i32_e32 v17, 0, v17
	v_fma_f32 v238, v16, v66, 0
	v_fma_f32 v239, v17, v67, 0
	v_max_i32_e32 v18, 0, v18
	v_max_i32_e32 v19, 0, v19
	v_fma_f32 v238, v18, v68, v238
	v_mfma_f32_32x32x16_f16 v[0:15], v[94:97], v[162:165], v[0:15]
	v_fma_f32 v239, v19, v69, v239
	v_max_i32_e32 v20, 0, v20
	v_max_i32_e32 v21, 0, v21
	v_fma_f32 v238, v20, v70, v238
	v_fma_f32 v239, v21, v71, v239
	v_max_i32_e32 v22, 0, v22
	v_max_i32_e32 v23, 0, v23
	v_mfma_f32_32x32x16_f16 v[0:15], v[98:101], v[158:161], v[0:15]
	v_fma_f32 v238, v22, v72, v238
	v_fma_f32 v239, v23, v73, v239
	v_max_i32_e32 v24, 0, v24
	v_max_i32_e32 v25, 0, v25
	v_fma_f32 v238, v24, v74, v238
	v_fma_f32 v239, v25, v75, v239
	v_mfma_f32_32x32x16_f16 v[0:15], v[102:105], v[154:157], v[0:15]
	v_max_i32_e32 v26, 0, v26
	v_max_i32_e32 v27, 0, v27
	v_fma_f32 v238, v26, v76, v238
	v_fma_f32 v239, v27, v77, v239
	v_max_i32_e32 v28, 0, v28
	v_max_i32_e32 v29, 0, v29
	v_mfma_f32_32x32x16_f16 v[0:15], v[106:109], v[150:153], v[0:15]
	v_fma_f32 v238, v28, v78, v238
	v_fma_f32 v239, v29, v79, v239
	v_max_i32_e32 v30, 0, v30
	v_max_i32_e32 v31, 0, v31
	v_fma_f32 v238, v30, v80, v238
	v_fma_f32 v239, v31, v81, v239
	v_mfma_f32_32x32x16_f16 v[0:15], v[110:113], v[146:149], v[0:15]
	v_add_f32_e32 v240, v238, v239
	v_mov_b32_e32 v241, v240
	v_lshlrev_b32_e32 v242, 2, v32
	s_nop 0
	v_permlane32_swap_b32_e32 v241, v240
	v_add_f32_e32 v241, v241, v240
	s_mov_b64 exec, s[4:5]
	global_store_dword v242, v241, s[24:25] offset:128
	s_mov_b64 exec, -1
	s_mov_b32 s98, 1
	s_add_i32 s47, s11, -3
	s_cmp_lt_u32 s47, s42
	s_cselect_b64 s[30:31], -1, 0
	s_cmp_ge_u32 s47, s42
	s_cbranch_scc1 .LBB0_1853
	s_waitcnt vmcnt(8)
	ds_write_b128 v209, v[134:137] offset:17408
	ds_write_b128 v209, v[142:145] offset:26112
.LBB0_1853:
	s_andn2_b64 vcc, exec, s[30:31]
	s_waitcnt lgkmcnt(0)
	s_barrier
	s_cbranch_vccnz .LBB0_1862
	s_cmp_gt_u32 s11, s42
	s_cbranch_scc1 .LBB0_1856
	v_add_co_u32_e32 v238, vcc, 0xffffe000, v178
	s_nop 1
	v_addc_co_u32_e32 v239, vcc, -1, v179, vcc
	global_load_dwordx4 v[134:137], v[238:239], off
	global_load_dwordx4 v[142:145], v[178:179], off
.LBB0_1856:
	ds_read_b128 v[250:253], v207 offset:17408
	ds_read_b128 v[210:213], v207 offset:17440
	ds_read_b128 v[214:217], v207 offset:17472
	ds_read_b128 v[218:221], v207 offset:17504
	ds_read_b128 v[222:225], v207 offset:17536
	ds_read_b128 v[226:229], v207 offset:17568
	ds_read_b128 v[230:233], v207 offset:17600
	ds_read_b128 v[234:237], v207 offset:17632
	ds_read_b128 v[174:177], v207 offset:26112
	ds_read_b128 v[170:173], v207 offset:26144
	ds_read_b128 v[166:169], v207 offset:26176
	ds_read_b128 v[162:165], v207 offset:26208
	ds_read_b128 v[158:161], v207 offset:26240
	ds_read_b128 v[154:157], v207 offset:26272
	ds_read_b128 v[150:153], v207 offset:26304
	ds_read_b128 v[146:149], v207 offset:26336
	s_cmp_eq_u32 s98, 0
	s_cbranch_scc1 .Lp11_skip3
	v_max_i32_e32 v0, 0, v0
	v_max_i32_e32 v1, 0, v1
	v_fma_f32 v243, v0, v114, 0
	v_fma_f32 v244, v1, v115, 0
	v_max_i32_e32 v2, 0, v2
	v_max_i32_e32 v3, 0, v3
	v_fma_f32 v243, v2, v116, v243
	v_fma_f32 v244, v3, v117, v244
	v_max_i32_e32 v4, 0, v4
	v_max_i32_e32 v5, 0, v5
	v_fma_f32 v243, v4, v118, v243
	v_fma_f32 v244, v5, v119, v244
	v_max_i32_e32 v6, 0, v6
	v_max_i32_e32 v7, 0, v7
	v_fma_f32 v243, v6, v120, v243
	v_fma_f32 v244, v7, v121, v244
	v_max_i32_e32 v8, 0, v8
	v_max_i32_e32 v9, 0, v9
	v_fma_f32 v243, v8, v122, v243
	v_fma_f32 v244, v9, v123, v244
	v_max_i32_e32 v10, 0, v10
	v_max_i32_e32 v11, 0, v11
	v_fma_f32 v243, v10, v124, v243
	v_fma_f32 v244, v11, v125, v244
	v_max_i32_e32 v12, 0, v12
	v_max_i32_e32 v13, 0, v13
	v_fma_f32 v243, v12, v126, v243
	v_fma_f32 v244, v13, v127, v244
	v_max_i32_e32 v14, 0, v14
	v_max_i32_e32 v15, 0, v15
	v_fma_f32 v243, v14, v128, v243
	v_fma_f32 v244, v15, v129, v244
	v_add_f32_e32 v245, v243, v244
	v_mov_b32_e32 v246, v245
	v_lshlrev_b32_e32 v247, 2, v32
	s_nop 0
	v_permlane32_swap_b32_e32 v246, v245
	v_add_f32_e32 v246, v246, v245
	s_mov_b64 exec, s[4:5]
	global_store_dword v247, v246, s[26:27] offset:128
	s_mov_b64 exec, -1
; DI void indexer_tile(const LAS unsigned char* buf, const f16x8 (&af)[2][8], const f32x4 (&wv)[2][4], float* sc0, float* sc1, int kt, int r32, int h2) {
;     ...
;     f16x8 bfr[2][8];
; #pragma unroll
;     for (int sub = 0; sub < 2; ++sub)
; #pragma unroll
;         for (int ks = 0; ks < 8; ++ks) bfr[sub][ks] = *(const LAS f16x8*)(buf + (32 * sub + r32) * KT_ROWB + (16 * ks + 8 * h2) * 2);
;     __builtin_amdgcn_sched_barrier(0);
; #pragma unroll
;     for (int sub = 0; sub < 2; ++sub) {
;         f32x16 c0, c1;
; #pragma unroll
;         for (int i = 0; i < 16; ++i) { c0[i] = 0.f; c1[i] = 0.f; }
; #pragma unroll
;         for (int ks = 0; ks < 8; ++ks) { c0 = __builtin_amdgcn_mfma_f32_32x32x16_f16(af[0][ks], bfr[sub][ks], c0, 0, 0, 0); c1 = __builtin_amdgcn_mfma_f32_32x32x16_f16(af[1][ks], bfr[sub][ks], c1, 0, 0, 0); }
;         f32x2_t a0 = {0.f, 0.f}, a1 = {0.f, 0.f};
; #pragma unroll
;         for (int q = 0; q < 4; ++q)
; #pragma unroll
;             for (int e = 0; e < 4; e += 2) {
;                 const f32x2_t r0 = {relu1(c0[4 * q + e]), relu1(c0[4 * q + e + 1])};
;                 const f32x2_t r1 = {relu1(c1[4 * q + e]), relu1(c1[4 * q + e + 1])};
;                 const f32x2_t w0 = {wv[0][q][e], wv[0][q][e + 1]}, w1 = {wv[1][q][e], wv[1][q][e + 1]};
; DI void indexer_phase(const unsigned short* QI, const unsigned short* KI16, const float* WI, float* SC, LAS unsigned char* lds, int tid, int bid, int G) {
;     ...
;             for (int kt = 0; kt < nt; kt += 2) {
;                 if (kt + 2 < nt) { const unsigned short* p = src + (size_t)(kt + 2) * 64 * 128; a0 = *(const u32x4*)p; a1 = *(const u32x4*)(p + 32 * 128); }
;                 indexer_tile(buf0, af, wv, sc0, sc1, kt, r32, h2);
;                 if (kt + 1 < nt) { *(LAS u32x4*)(buf1 + key0 * KT_ROWB + ch * 16) = b0; *(LAS u32x4*)(buf1 + (key0 + 32) * KT_ROWB + ch * 16) = b1; }
;                 __syncthreads();
;                 if (kt + 1 >= nt) break;
;                 if (kt + 3 < nt) { const unsigned short* p = src + (size_t)(kt + 3) * 64 * 128; b0 = *(const u32x4*)p; b1 = *(const u32x4*)(p + 32 * 128); }
;                 indexer_tile(buf1, af, wv, sc0, sc1, kt + 1, r32, h2);
;                 if (kt + 2 < nt) { *(LAS u32x4*)(buf0 + key0 * KT_ROWB + ch * 16) = a0; *(LAS u32x4*)(buf0 + (key0 + 32) * KT_ROWB + ch * 16) = a1; }
;                 __syncthreads();
.Lp11_skip3:
	s_waitcnt lgkmcnt(15)
	v_mfma_f32_32x32x16_f16 v[16:31], v[34:37], v[250:253], 0
	s_waitcnt lgkmcnt(14)
	v_mfma_f32_32x32x16_f16 v[16:31], v[38:41], v[210:213], v[16:31]
	s_waitcnt lgkmcnt(13)
	v_mfma_f32_32x32x16_f16 v[16:31], v[42:45], v[214:217], v[16:31]
	s_waitcnt lgkmcnt(12)
	v_mfma_f32_32x32x16_f16 v[16:31], v[46:49], v[218:221], v[16:31]
	s_waitcnt lgkmcnt(11)
	v_mfma_f32_32x32x16_f16 v[16:31], v[50:53], v[222:225], v[16:31]
	s_waitcnt lgkmcnt(10)
	v_mfma_f32_32x32x16_f16 v[16:31], v[54:57], v[226:229], v[16:31]
	s_waitcnt lgkmcnt(9)
	v_mfma_f32_32x32x16_f16 v[16:31], v[58:61], v[230:233], v[16:31]
	s_waitcnt lgkmcnt(8)
	v_mfma_f32_32x32x16_f16 v[16:31], v[62:65], v[234:237], v[16:31]
	v_mfma_f32_32x32x16_f16 v[0:15], v[82:85], v[250:253], 0
	v_mfma_f32_32x32x16_f16 v[0:15], v[86:89], v[210:213], v[0:15]
	v_mfma_f32_32x32x16_f16 v[0:15], v[90:93], v[214:217], v[0:15]
	s_nop 8
	v_max_i32_e32 v16, 0, v16
	v_max_i32_e32 v17, 0, v17
	v_fma_f32 v238, v16, v66, 0
	v_fma_f32 v239, v17, v67, 0
	v_max_i32_e32 v18, 0, v18
	v_max_i32_e32 v19, 0, v19
	v_fma_f32 v238, v18, v68, v238
	v_mfma_f32_32x32x16_f16 v[0:15], v[94:97], v[218:221], v[0:15]
	v_fma_f32 v239, v19, v69, v239
	v_max_i32_e32 v20, 0, v20
	v_max_i32_e32 v21, 0, v21
	v_fma_f32 v238, v20, v70, v238
	v_fma_f32 v239, v21, v71, v239
	v_max_i32_e32 v22, 0, v22
	v_max_i32_e32 v23, 0, v23
	v_mfma_f32_32x32x16_f16 v[0:15], v[98:101], v[222:225], v[0:15]
	v_fma_f32 v238, v22, v72, v238
	v_fma_f32 v239, v23, v73, v239
	v_max_i32_e32 v24, 0, v24
	v_max_i32_e32 v25, 0, v25
	v_fma_f32 v238, v24, v74, v238
	v_fma_f32 v239, v25, v75, v239
	v_mfma_f32_32x32x16_f16 v[0:15], v[102:105], v[226:229], v[0:15]
	v_max_i32_e32 v26, 0, v26
	v_max_i32_e32 v27, 0, v27
	v_fma_f32 v238, v26, v76, v238
	v_fma_f32 v239, v27, v77, v239
	v_max_i32_e32 v28, 0, v28
	v_max_i32_e32 v29, 0, v29
	v_mfma_f32_32x32x16_f16 v[0:15], v[106:109], v[230:233], v[0:15]
	v_fma_f32 v238, v28, v78, v238
	v_fma_f32 v239, v29, v79, v239
	v_max_i32_e32 v30, 0, v30
	v_max_i32_e32 v31, 0, v31
	v_fma_f32 v238, v30, v80, v238
	v_fma_f32 v239, v31, v81, v239
	v_mfma_f32_32x32x16_f16 v[0:15], v[110:113], v[234:237], v[0:15]
	v_add_f32_e32 v240, v238, v239
	v_mov_b32_e32 v241, v240
	v_lshlrev_b32_e32 v242, 2, v32
	s_nop 0
	v_permlane32_swap_b32_e32 v241, v240
	v_add_f32_e32 v241, v241, v240
	s_mov_b64 exec, s[4:5]
	global_store_dword v242, v241, s[24:25] offset:256
	s_mov_b64 exec, -1
	s_waitcnt lgkmcnt(0)
	v_mfma_f32_32x32x16_f16 v[16:31], v[34:37], v[174:177], 0
	v_mfma_f32_32x32x16_f16 v[16:31], v[38:41], v[170:173], v[16:31]
	v_mfma_f32_32x32x16_f16 v[16:31], v[42:45], v[166:169], v[16:31]
	s_nop 8
	v_max_i32_e32 v0, 0, v0
	v_max_i32_e32 v1, 0, v1
	v_fma_f32 v243, v0, v114, 0
	v_fma_f32 v244, v1, v115, 0
	v_max_i32_e32 v2, 0, v2
	v_max_i32_e32 v3, 0, v3
	v_fma_f32 v243, v2, v116, v243
	v_mfma_f32_32x32x16_f16 v[16:31], v[46:49], v[162:165], v[16:31]
	v_fma_f32 v244, v3, v117, v244
	v_max_i32_e32 v4, 0, v4
	v_max_i32_e32 v5, 0, v5
	v_fma_f32 v243, v4, v118, v243
	v_fma_f32 v244, v5, v119, v244
	v_max_i32_e32 v6, 0, v6
	v_max_i32_e32 v7, 0, v7
	v_mfma_f32_32x32x16_f16 v[16:31], v[50:53], v[158:161], v[16:31]
	v_fma_f32 v243, v6, v120, v243
	v_fma_f32 v244, v7, v121, v244
	v_max_i32_e32 v8, 0, v8
	v_max_i32_e32 v9, 0, v9
	v_fma_f32 v243, v8, v122, v243
	v_fma_f32 v244, v9, v123, v244
	v_mfma_f32_32x32x16_f16 v[16:31], v[54:57], v[154:157], v[16:31]
	v_max_i32_e32 v10, 0, v10
	v_max_i32_e32 v11, 0, v11
	v_fma_f32 v243, v10, v124, v243
	v_fma_f32 v244, v11, v125, v244
	v_max_i32_e32 v12, 0, v12
	v_max_i32_e32 v13, 0, v13
	v_mfma_f32_32x32x16_f16 v[16:31], v[58:61], v[150:153], v[16:31]
	v_fma_f32 v243, v12, v126, v243
	v_fma_f32 v244, v13, v127, v244
	v_max_i32_e32 v14, 0, v14
	v_max_i32_e32 v15, 0, v15
	v_fma_f32 v243, v14, v128, v243
	v_fma_f32 v244, v15, v129, v244
	v_mfma_f32_32x32x16_f16 v[16:31], v[62:65], v[146:149], v[16:31]
	v_add_f32_e32 v245, v243, v244
	v_mov_b32_e32 v246, v245
	v_lshlrev_b32_e32 v247, 2, v32
	s_nop 0
	v_permlane32_swap_b32_e32 v246, v245
	v_add_f32_e32 v246, v246, v245
	s_mov_b64 exec, s[4:5]
	global_store_dword v247, v246, s[26:27] offset:256
	s_mov_b64 exec, -1
	v_mfma_f32_32x32x16_f16 v[0:15], v[82:85], v[174:177], 0
	v_mfma_f32_32x32x16_f16 v[0:15], v[86:89], v[170:173], v[0:15]
	v_mfma_f32_32x32x16_f16 v[0:15], v[90:93], v[166:169], v[0:15]
	s_nop 8
	v_max_i32_e32 v16, 0, v16
	v_max_i32_e32 v17, 0, v17
	v_fma_f32 v238, v16, v66, 0
	v_fma_f32 v239, v17, v67, 0
	v_max_i32_e32 v18, 0, v18
	v_max_i32_e32 v19, 0, v19
	v_fma_f32 v238, v18, v68, v238
	v_mfma_f32_32x32x16_f16 v[0:15], v[94:97], v[162:165], v[0:15]
	v_fma_f32 v239, v19, v69, v239
	v_max_i32_e32 v20, 0, v20
	v_max_i32_e32 v21, 0, v21
	v_fma_f32 v238, v20, v70, v238
	v_fma_f32 v239, v21, v71, v239
	v_max_i32_e32 v22, 0, v22
	v_max_i32_e32 v23, 0, v23
	v_mfma_f32_32x32x16_f16 v[0:15], v[98:101], v[158:161], v[0:15]
	v_fma_f32 v238, v22, v72, v238
	v_fma_f32 v239, v23, v73, v239
	v_max_i32_e32 v24, 0, v24
	v_max_i32_e32 v25, 0, v25
	v_fma_f32 v238, v24, v74, v238
	v_fma_f32 v239, v25, v75, v239
	v_mfma_f32_32x32x16_f16 v[0:15], v[102:105], v[154:157], v[0:15]
	v_max_i32_e32 v26, 0, v26
	v_max_i32_e32 v27, 0, v27
	v_fma_f32 v238, v26, v76, v238
	v_fma_f32 v239, v27, v77, v239
	v_max_i32_e32 v28, 0, v28
	v_max_i32_e32 v29, 0, v29
	v_mfma_f32_32x32x16_f16 v[0:15], v[106:109], v[150:153], v[0:15]
	v_fma_f32 v238, v28, v78, v238
	v_fma_f32 v239, v29, v79, v239
	v_max_i32_e32 v30, 0, v30
	v_max_i32_e32 v31, 0, v31
	v_fma_f32 v238, v30, v80, v238
	v_fma_f32 v239, v31, v81, v239
	v_mfma_f32_32x32x16_f16 v[0:15], v[110:113], v[146:149], v[0:15]
	v_add_f32_e32 v240, v238, v239
	v_mov_b32_e32 v241, v240
	v_lshlrev_b32_e32 v242, 2, v32
	s_nop 0
	v_permlane32_swap_b32_e32 v241, v240
	v_add_f32_e32 v241, v241, v240
	s_mov_b64 exec, s[4:5]
	global_store_dword v242, v241, s[24:25] offset:384
	s_mov_b64 exec, -1
	s_mov_b32 s98, 1
	s_andn2_b64 vcc, exec, s[28:29]
	s_cbranch_vccnz .LBB0_1844
	s_waitcnt vmcnt(7)
	ds_write_b128 v209, v[130:133]
	ds_write_b128 v209, v[138:141] offset:8704
	s_branch .LBB0_1844
; DI void indexer_tile(const LAS unsigned char* buf, const f16x8 (&af)[2][8], const f32x4 (&wv)[2][4], float* sc0, float* sc1, int kt, int r32, int h2) {
;     ...
;                 const f32x2_t r0 = {relu1(c0[4 * q + e]), relu1(c0[4 * q + e + 1])};
;                 const f32x2_t r1 = {relu1(c1[4 * q + e]), relu1(c1[4 * q + e + 1])};
;                 const f32x2_t w0 = {wv[0][q][e], wv[0][q][e + 1]}, w1 = {wv[1][q][e], wv[1][q][e + 1]};
;                 a0 = __builtin_elementwise_fma(r0, w0, a0); a1 = __builtin_elementwise_fma(r1, w1, a1); }
;         float s0 = a0.x + a0.y, s1 = a1.x + a1.y;
;         s0 += __shfl_xor(s0, 32); s1 += __shfl_xor(s1, 32);
;         if (h2 == 0) { sc0[kt * 64 + 32 * sub + r32] = s0; sc1[kt * 64 + 32 * sub + r32] = s1; }
; DI void indexer_phase(const unsigned short* QI, const unsigned short* KI16, const float* WI, float* SC, LAS unsigned char* lds, int tid, int bid, int G) {
;     ...
;                 __syncthreads();
;                 if (kt + 1 >= nt) break;
.LBB0_1862:
	v_max_i32_e32 v0, 0, v0
	v_max_i32_e32 v1, 0, v1
	v_fma_f32 v243, v0, v114, 0
	v_fma_f32 v244, v1, v115, 0
	v_max_i32_e32 v2, 0, v2
	v_max_i32_e32 v3, 0, v3
	v_fma_f32 v243, v2, v116, v243
	v_fma_f32 v244, v3, v117, v244
	v_max_i32_e32 v4, 0, v4
	v_max_i32_e32 v5, 0, v5
	v_fma_f32 v243, v4, v118, v243
	v_fma_f32 v244, v5, v119, v244
	v_max_i32_e32 v6, 0, v6
	v_max_i32_e32 v7, 0, v7
	v_fma_f32 v243, v6, v120, v243
	v_fma_f32 v244, v7, v121, v244
	v_max_i32_e32 v8, 0, v8
	v_max_i32_e32 v9, 0, v9
	v_fma_f32 v243, v8, v122, v243
	v_fma_f32 v244, v9, v123, v244
	v_max_i32_e32 v10, 0, v10
	v_max_i32_e32 v11, 0, v11
	v_fma_f32 v243, v10, v124, v243
	v_fma_f32 v244, v11, v125, v244
	v_max_i32_e32 v12, 0, v12
	v_max_i32_e32 v13, 0, v13
	v_fma_f32 v243, v12, v126, v243
	v_fma_f32 v244, v13, v127, v244
	v_max_i32_e32 v14, 0, v14
	v_max_i32_e32 v15, 0, v15
	v_fma_f32 v243, v14, v128, v243
	v_fma_f32 v244, v15, v129, v244
	v_add_f32_e32 v245, v243, v244
	v_mov_b32_e32 v246, v245
	v_lshlrev_b32_e32 v247, 2, v32
	s_nop 0
	v_permlane32_swap_b32_e32 v246, v245
	v_add_f32_e32 v246, v246, v245
	s_mov_b64 exec, s[4:5]
	global_store_dword v247, v246, s[26:27] offset:128
	s_mov_b64 exec, -1
	s_mov_b32 s98, 0
	s_cbranch_execz .LBB0_1845

; #define LAS __attribute__((address_space(3)))
; DI size_t sc_row_off(int b, int s) { const int qb = s >> 7; return ((size_t)(b * 2080 + ((qb * (qb + 1)) >> 1))) * 16384 + (size_t)(s & 127) * ((qb + 1) * 128); }
; DI void indexer_tile(const LAS unsigned char* buf, const f16x8 (&af)[2][8], const f32x4 (&wv)[2][4], float* sc0, float* sc1, int kt, int r32, int h2) {
;     ...
;                 const f32x2_t r0 = {relu1(c0[4 * q + e]), relu1(c0[4 * q + e + 1])};
;                 const f32x2_t r1 = {relu1(c1[4 * q + e]), relu1(c1[4 * q + e + 1])};
;                 const f32x2_t w0 = {wv[0][q][e], wv[0][q][e + 1]}, w1 = {wv[1][q][e], wv[1][q][e + 1]};
;                 a0 = __builtin_elementwise_fma(r0, w0, a0); a1 = __builtin_elementwise_fma(r1, w1, a1); }
;         float s0 = a0.x + a0.y, s1 = a1.x + a1.y;
;         s0 += __shfl_xor(s0, 32); s1 += __shfl_xor(s1, 32);
;         if (h2 == 0) { sc0[kt * 64 + 32 * sub + r32] = s0; sc1[kt * 64 + 32 * sub + r32] = s1; }
; DI void indexer_phase(const unsigned short* QI, const unsigned short* KI16, const float* WI, float* SC, LAS unsigned char* lds, int tid, int bid, int G) {
;     ...
;             float* sc0 = SC + sc_row_off(b, tb + 2 * w); float* sc1 = SC + sc_row_off(b, tb + 2 * w + 1);
;             const unsigned short* src = KI16 + (size_t)b * SEQ * 128 + (size_t)key0 * 128 + ch * 8;
;             u32x4 a0, a1, b0 = {0u, 0u, 0u, 0u}, b1 = {0u, 0u, 0u, 0u};
;             a0 = *(const u32x4*)src; a1 = *(const u32x4*)(src + 32 * 128);
;             if (nt > 1) { b0 = *(const u32x4*)(src + 64 * 128); b1 = *(const u32x4*)(src + 96 * 128); }
;             __syncthreads();
;             *(LAS u32x4*)(buf0 + key0 * KT_ROWB + ch * 16) = a0; *(LAS u32x4*)(buf0 + (key0 + 32) * KT_ROWB + ch * 16) = a1;
;             __syncthreads();
.LBB0_1866:
	s_andn2_b64 vcc, exec, s[14:15]
	s_barrier
	s_waitcnt vmcnt(1)
	ds_write_b128 v209, v[132:135]
	s_waitcnt vmcnt(0)
	ds_write_b128 v209, v[136:139] offset:8704
	s_waitcnt lgkmcnt(0)
	s_barrier
	s_cbranch_vccnz .LBB0_1887
	s_ashr_i32 s11, s10, 31
	s_lshl_b64 s[10:11], s[10:11], 16
	s_add_u32 s10, s17, s10
	s_addc_u32 s11, s33, s11
	s_add_u32 s10, s10, 0x8200000
	s_addc_u32 s11, s11, 0
	s_lshl_b64 s[6:7], s[6:7], 2
	s_add_u32 s6, s10, s6
	s_addc_u32 s7, s11, s7
	s_lshl_b64 s[8:9], s[8:9], 2
	s_add_u32 s8, s10, s8
	s_addc_u32 s9, s11, s9
	s_mov_b32 s14, 3
	v_mov_b32_e32 v32, v206
	v_mov_b64_e32 v[34:35], v[202:203]
	s_mov_b32 s98, 0
	s_branch .LBB0_1869
.Lp11_fb2:
	v_max_i32_e32 v0, 0, v0
	v_max_i32_e32 v1, 0, v1
	v_fma_f32 v243, v0, v116, 0
	v_fma_f32 v244, v1, v117, 0
	v_max_i32_e32 v2, 0, v2
	v_max_i32_e32 v3, 0, v3
	v_fma_f32 v243, v2, v118, v243
	v_fma_f32 v244, v3, v119, v244
	v_max_i32_e32 v4, 0, v4
	v_max_i32_e32 v5, 0, v5
	v_fma_f32 v243, v4, v120, v243
	v_fma_f32 v244, v5, v121, v244
	v_max_i32_e32 v6, 0, v6
	v_max_i32_e32 v7, 0, v7
	v_fma_f32 v243, v6, v122, v243
	v_fma_f32 v244, v7, v123, v244
	v_max_i32_e32 v8, 0, v8
	v_max_i32_e32 v9, 0, v9
	v_fma_f32 v243, v8, v124, v243
	v_fma_f32 v244, v9, v125, v244
	v_max_i32_e32 v10, 0, v10
	v_max_i32_e32 v11, 0, v11
	v_fma_f32 v243, v10, v126, v243
	v_fma_f32 v244, v11, v127, v244
	v_max_i32_e32 v12, 0, v12
	v_max_i32_e32 v13, 0, v13
	v_fma_f32 v243, v12, v128, v243
	v_fma_f32 v244, v13, v129, v244
	v_max_i32_e32 v14, 0, v14
	v_max_i32_e32 v15, 0, v15
	v_fma_f32 v243, v14, v130, v243
	v_fma_f32 v244, v15, v131, v244
	v_add_f32_e32 v245, v243, v244
	v_mov_b32_e32 v246, v245
	v_lshlrev_b32_e32 v247, 2, v32
	s_nop 0
	v_permlane32_swap_b32_e32 v246, v245
	v_add_f32_e32 v246, v246, v245
	s_mov_b64 exec, s[4:5]
	global_store_dword v247, v246, s[8:9] offset:-128
	s_mov_b64 exec, -1
	s_mov_b32 s98, 0
	s_branch .LBB0_1887

; #define LAS __attribute__((address_space(3)))
; DI void indexer_tile(const LAS unsigned char* buf, const f16x8 (&af)[2][8], const f32x4 (&wv)[2][4], float* sc0, float* sc1, int kt, int r32, int h2) {
;     ...
;     f16x8 bfr[2][8];
; #pragma unroll
;     for (int sub = 0; sub < 2; ++sub)
; #pragma unroll
;         for (int ks = 0; ks < 8; ++ks) bfr[sub][ks] = *(const LAS f16x8*)(buf + (32 * sub + r32) * KT_ROWB + (16 * ks + 8 * h2) * 2);
;     __builtin_amdgcn_sched_barrier(0);
; #pragma unroll
;     for (int sub = 0; sub < 2; ++sub) {
;         f32x16 c0, c1;
; #pragma unroll
;         for (int i = 0; i < 16; ++i) { c0[i] = 0.f; c1[i] = 0.f; }
; #pragma unroll
;         for (int ks = 0; ks < 8; ++ks) { c0 = __builtin_amdgcn_mfma_f32_32x32x16_f16(af[0][ks], bfr[sub][ks], c0, 0, 0, 0); c1 = __builtin_amdgcn_mfma_f32_32x32x16_f16(af[1][ks], bfr[sub][ks], c1, 0, 0, 0); }
;         f32x2_t a0 = {0.f, 0.f}, a1 = {0.f, 0.f};
; #pragma unroll
;         for (int q = 0; q < 4; ++q)
; #pragma unroll
;             for (int e = 0; e < 4; e += 2) {
;                 const f32x2_t r0 = {relu1(c0[4 * q + e]), relu1(c0[4 * q + e + 1])};
;                 const f32x2_t r1 = {relu1(c1[4 * q + e]), relu1(c1[4 * q + e + 1])};
;                 const f32x2_t w0 = {wv[0][q][e], wv[0][q][e + 1]}, w1 = {wv[1][q][e], wv[1][q][e + 1]};
;                 a0 = __builtin_elementwise_fma(r0, w0, a0); a1 = __builtin_elementwise_fma(r1, w1, a1); }
;         float s0 = a0.x + a0.y, s1 = a1.x + a1.y;
;         s0 += __shfl_xor(s0, 32); s1 += __shfl_xor(s1, 32);
;         if (h2 == 0) { sc0[kt * 64 + 32 * sub + r32] = s0; sc1[kt * 64 + 32 * sub + r32] = s1; }
;     }
; DI void indexer_phase(const unsigned short* QI, const unsigned short* KI16, const float* WI, float* SC, LAS unsigned char* lds, int tid, int bid, int G) {
;     ...
;             for (int kt = 0; kt < nt; kt += 2) {
;                 if (kt + 2 < nt) { const unsigned short* p = src + (size_t)(kt + 2) * 64 * 128; a0 = *(const u32x4*)p; a1 = *(const u32x4*)(p + 32 * 128); }
;                 indexer_tile(buf0, af, wv, sc0, sc1, kt, r32, h2);
.LBB0_1869:
	s_add_i32 s15, s14, -1
	s_cmp_le_i32 s15, s41
	s_cselect_b64 s[10:11], -1, 0
	s_cmp_gt_i32 s15, s41
	s_cbranch_scc1 .LBB0_1871
	v_add_co_u32_e32 v238, vcc, 0xffffa000, v34
	s_nop 1
	v_addc_co_u32_e32 v239, vcc, -1, v35, vcc
	v_add_co_u32_e32 v240, vcc, 0xffffc000, v34
	s_nop 1
	v_addc_co_u32_e32 v241, vcc, -1, v35, vcc
	global_load_dwordx4 v[132:135], v[238:239], off
	global_load_dwordx4 v[136:139], v[240:241], off
.LBB0_1871:
	ds_read_b128 v[250:253], v207
	ds_read_b128 v[210:213], v207 offset:32
	ds_read_b128 v[214:217], v207 offset:64
	ds_read_b128 v[218:221], v207 offset:96
	ds_read_b128 v[222:225], v207 offset:128
	ds_read_b128 v[226:229], v207 offset:160
	ds_read_b128 v[230:233], v207 offset:192
	ds_read_b128 v[234:237], v207 offset:224
	ds_read_b128 v[176:179], v207 offset:8704
	ds_read_b128 v[172:175], v207 offset:8736
	ds_read_b128 v[168:171], v207 offset:8768
	ds_read_b128 v[164:167], v207 offset:8800
	ds_read_b128 v[160:163], v207 offset:8832
	ds_read_b128 v[156:159], v207 offset:8864
	ds_read_b128 v[152:155], v207 offset:8896
	ds_read_b128 v[148:151], v207 offset:8928
	s_cmp_eq_u32 s98, 0
	s_cbranch_scc1 .Lp11_skip4
	v_max_i32_e32 v0, 0, v0
	v_max_i32_e32 v1, 0, v1
	v_fma_f32 v243, v0, v116, 0
	v_fma_f32 v244, v1, v117, 0
	v_max_i32_e32 v2, 0, v2
	v_max_i32_e32 v3, 0, v3
	v_fma_f32 v243, v2, v118, v243
	v_fma_f32 v244, v3, v119, v244
	v_max_i32_e32 v4, 0, v4
	v_max_i32_e32 v5, 0, v5
	v_fma_f32 v243, v4, v120, v243
	v_fma_f32 v244, v5, v121, v244
	v_max_i32_e32 v6, 0, v6
	v_max_i32_e32 v7, 0, v7
	v_fma_f32 v243, v6, v122, v243
	v_fma_f32 v244, v7, v123, v244
	v_max_i32_e32 v8, 0, v8
	v_max_i32_e32 v9, 0, v9
	v_fma_f32 v243, v8, v124, v243
	v_fma_f32 v244, v9, v125, v244
	v_max_i32_e32 v10, 0, v10
	v_max_i32_e32 v11, 0, v11
	v_fma_f32 v243, v10, v126, v243
	v_fma_f32 v244, v11, v127, v244
	v_max_i32_e32 v12, 0, v12
	v_max_i32_e32 v13, 0, v13
	v_fma_f32 v243, v12, v128, v243
	v_fma_f32 v244, v13, v129, v244
	v_max_i32_e32 v14, 0, v14
	v_max_i32_e32 v15, 0, v15
	v_fma_f32 v243, v14, v130, v243
	v_fma_f32 v244, v15, v131, v244
	v_add_f32_e32 v245, v243, v244
	v_mov_b32_e32 v246, v245
	v_lshlrev_b32_e32 v247, 2, v32
	s_nop 0
	v_permlane32_swap_b32_e32 v246, v245
	v_add_f32_e32 v246, v246, v245
	s_mov_b64 exec, s[4:5]
	global_store_dword v247, v246, s[8:9] offset:-128
	s_mov_b64 exec, -1
.Lp11_skip4:
	s_waitcnt lgkmcnt(15)
	v_mfma_f32_32x32x16_f16 v[16:31], v[36:39], v[250:253], 0
	s_waitcnt lgkmcnt(14)
	v_mfma_f32_32x32x16_f16 v[16:31], v[40:43], v[210:213], v[16:31]
	s_waitcnt lgkmcnt(13)
	v_mfma_f32_32x32x16_f16 v[16:31], v[44:47], v[214:217], v[16:31]
	s_waitcnt lgkmcnt(12)
	v_mfma_f32_32x32x16_f16 v[16:31], v[48:51], v[218:221], v[16:31]
	s_waitcnt lgkmcnt(11)
	v_mfma_f32_32x32x16_f16 v[16:31], v[52:55], v[222:225], v[16:31]
	s_waitcnt lgkmcnt(10)
	v_mfma_f32_32x32x16_f16 v[16:31], v[56:59], v[226:229], v[16:31]
	s_waitcnt lgkmcnt(9)
	v_mfma_f32_32x32x16_f16 v[16:31], v[60:63], v[230:233], v[16:31]
	s_waitcnt lgkmcnt(8)
	v_mfma_f32_32x32x16_f16 v[16:31], v[64:67], v[234:237], v[16:31]
	v_mfma_f32_32x32x16_f16 v[0:15], v[84:87], v[250:253], 0
	v_mfma_f32_32x32x16_f16 v[0:15], v[88:91], v[210:213], v[0:15]
	v_mfma_f32_32x32x16_f16 v[0:15], v[92:95], v[214:217], v[0:15]
	s_nop 8
	v_max_i32_e32 v16, 0, v16
	v_max_i32_e32 v17, 0, v17
	v_fma_f32 v238, v16, v68, 0
	v_fma_f32 v239, v17, v69, 0
	v_max_i32_e32 v18, 0, v18
	v_max_i32_e32 v19, 0, v19
	v_fma_f32 v238, v18, v70, v238
	v_mfma_f32_32x32x16_f16 v[0:15], v[96:99], v[218:221], v[0:15]
	v_fma_f32 v239, v19, v71, v239
	v_max_i32_e32 v20, 0, v20
	v_max_i32_e32 v21, 0, v21
	v_fma_f32 v238, v20, v72, v238
	v_fma_f32 v239, v21, v73, v239
	v_max_i32_e32 v22, 0, v22
	v_max_i32_e32 v23, 0, v23
	v_mfma_f32_32x32x16_f16 v[0:15], v[100:103], v[222:225], v[0:15]
	v_fma_f32 v238, v22, v74, v238
	v_fma_f32 v239, v23, v75, v239
	v_max_i32_e32 v24, 0, v24
	v_max_i32_e32 v25, 0, v25
	v_fma_f32 v238, v24, v76, v238
	v_fma_f32 v239, v25, v77, v239
	v_mfma_f32_32x32x16_f16 v[0:15], v[104:107], v[226:229], v[0:15]
	v_max_i32_e32 v26, 0, v26
	v_max_i32_e32 v27, 0, v27
	v_fma_f32 v238, v26, v78, v238
	v_fma_f32 v239, v27, v79, v239
	v_max_i32_e32 v28, 0, v28
	v_max_i32_e32 v29, 0, v29
	v_mfma_f32_32x32x16_f16 v[0:15], v[108:111], v[230:233], v[0:15]
	v_fma_f32 v238, v28, v80, v238
	v_fma_f32 v239, v29, v81, v239
	v_max_i32_e32 v30, 0, v30
	v_max_i32_e32 v31, 0, v31
	v_fma_f32 v238, v30, v82, v238
	v_fma_f32 v239, v31, v83, v239
	v_mfma_f32_32x32x16_f16 v[0:15], v[112:115], v[234:237], v[0:15]
	v_add_f32_e32 v240, v238, v239
	v_mov_b32_e32 v241, v240
	v_lshlrev_b32_e32 v242, 2, v32
	s_nop 0
	v_permlane32_swap_b32_e32 v241, v240
	v_add_f32_e32 v241, v241, v240
	s_mov_b64 exec, s[4:5]
	global_store_dword v242, v241, s[6:7]
	s_mov_b64 exec, -1
	s_waitcnt lgkmcnt(0)
; #define LAS __attribute__((address_space(3)))
; DI void indexer_tile(const LAS unsigned char* buf, const f16x8 (&af)[2][8], const f32x4 (&wv)[2][4], float* sc0, float* sc1, int kt, int r32, int h2) {
;     ...
;     f16x8 bfr[2][8];
; #pragma unroll
;     for (int sub = 0; sub < 2; ++sub)
; #pragma unroll
;         for (int ks = 0; ks < 8; ++ks) bfr[sub][ks] = *(const LAS f16x8*)(buf + (32 * sub + r32) * KT_ROWB + (16 * ks + 8 * h2) * 2);
;     __builtin_amdgcn_sched_barrier(0);
; #pragma unroll
;     for (int sub = 0; sub < 2; ++sub) {
;         f32x16 c0, c1;
; #pragma unroll
;         for (int i = 0; i < 16; ++i) { c0[i] = 0.f; c1[i] = 0.f; }
; #pragma unroll
;         for (int ks = 0; ks < 8; ++ks) { c0 = __builtin_amdgcn_mfma_f32_32x32x16_f16(af[0][ks], bfr[sub][ks], c0, 0, 0, 0); c1 = __builtin_amdgcn_mfma_f32_32x32x16_f16(af[1][ks], bfr[sub][ks], c1, 0, 0, 0); }
;         f32x2_t a0 = {0.f, 0.f}, a1 = {0.f, 0.f};
; #pragma unroll
;         for (int q = 0; q < 4; ++q)
; #pragma unroll
;             for (int e = 0; e < 4; e += 2) {
;                 const f32x2_t r0 = {relu1(c0[4 * q + e]), relu1(c0[4 * q + e + 1])};
;                 const f32x2_t r1 = {relu1(c1[4 * q + e]), relu1(c1[4 * q + e + 1])};
;                 const f32x2_t w0 = {wv[0][q][e], wv[0][q][e + 1]}, w1 = {wv[1][q][e], wv[1][q][e + 1]};
;                 a0 = __builtin_elementwise_fma(r0, w0, a0); a1 = __builtin_elementwise_fma(r1, w1, a1); }
;         float s0 = a0.x + a0.y, s1 = a1.x + a1.y;
;         s0 += __shfl_xor(s0, 32); s1 += __shfl_xor(s1, 32);
;         if (h2 == 0) { sc0[kt * 64 + 32 * sub + r32] = s0; sc1[kt * 64 + 32 * sub + r32] = s1; }
;     }
; DI void indexer_phase(const unsigned short* QI, const unsigned short* KI16, const float* WI, float* SC, LAS unsigned char* lds, int tid, int bid, int G) {
;     ...
;                 indexer_tile(buf0, af, wv, sc0, sc1, kt, r32, h2);
;                 if (kt + 1 < nt) { *(LAS u32x4*)(buf1 + key0 * KT_ROWB + ch * 16) = b0; *(LAS u32x4*)(buf1 + (key0 + 32) * KT_ROWB + ch * 16) = b1; }
	v_mfma_f32_32x32x16_f16 v[16:31], v[36:39], v[176:179], 0
	v_mfma_f32_32x32x16_f16 v[16:31], v[40:43], v[172:175], v[16:31]
	v_mfma_f32_32x32x16_f16 v[16:31], v[44:47], v[168:171], v[16:31]
	s_nop 8
	v_max_i32_e32 v0, 0, v0
	v_max_i32_e32 v1, 0, v1
	v_fma_f32 v243, v0, v116, 0
	v_fma_f32 v244, v1, v117, 0
	v_max_i32_e32 v2, 0, v2
	v_max_i32_e32 v3, 0, v3
	v_fma_f32 v243, v2, v118, v243
	v_mfma_f32_32x32x16_f16 v[16:31], v[48:51], v[164:167], v[16:31]
	v_fma_f32 v244, v3, v119, v244
	v_max_i32_e32 v4, 0, v4
	v_max_i32_e32 v5, 0, v5
	v_fma_f32 v243, v4, v120, v243
	v_fma_f32 v244, v5, v121, v244
	v_max_i32_e32 v6, 0, v6
	v_max_i32_e32 v7, 0, v7
	v_mfma_f32_32x32x16_f16 v[16:31], v[52:55], v[160:163], v[16:31]
	v_fma_f32 v243, v6, v122, v243
	v_fma_f32 v244, v7, v123, v244
	v_max_i32_e32 v8, 0, v8
	v_max_i32_e32 v9, 0, v9
	v_fma_f32 v243, v8, v124, v243
	v_fma_f32 v244, v9, v125, v244
	v_mfma_f32_32x32x16_f16 v[16:31], v[56:59], v[156:159], v[16:31]
	v_max_i32_e32 v10, 0, v10
	v_max_i32_e32 v11, 0, v11
	v_fma_f32 v243, v10, v126, v243
	v_fma_f32 v244, v11, v127, v244
	v_max_i32_e32 v12, 0, v12
	v_max_i32_e32 v13, 0, v13
	v_mfma_f32_32x32x16_f16 v[16:31], v[60:63], v[152:155], v[16:31]
	v_fma_f32 v243, v12, v128, v243
	v_fma_f32 v244, v13, v129, v244
	v_max_i32_e32 v14, 0, v14
	v_max_i32_e32 v15, 0, v15
	v_fma_f32 v243, v14, v130, v243
	v_fma_f32 v244, v15, v131, v244
	v_mfma_f32_32x32x16_f16 v[16:31], v[64:67], v[148:151], v[16:31]
	v_add_f32_e32 v245, v243, v244
	v_mov_b32_e32 v246, v245
	v_lshlrev_b32_e32 v247, 2, v32
	s_nop 0
	v_permlane32_swap_b32_e32 v246, v245
	v_add_f32_e32 v246, v246, v245
	s_mov_b64 exec, s[4:5]
	global_store_dword v247, v246, s[8:9]
	s_mov_b64 exec, -1
	v_mfma_f32_32x32x16_f16 v[0:15], v[84:87], v[176:179], 0
	v_mfma_f32_32x32x16_f16 v[0:15], v[88:91], v[172:175], v[0:15]
	v_mfma_f32_32x32x16_f16 v[0:15], v[92:95], v[168:171], v[0:15]
	s_nop 8
	v_max_i32_e32 v16, 0, v16
	v_max_i32_e32 v17, 0, v17
	v_fma_f32 v238, v16, v68, 0
	v_fma_f32 v239, v17, v69, 0
	v_max_i32_e32 v18, 0, v18
	v_max_i32_e32 v19, 0, v19
	v_fma_f32 v238, v18, v70, v238
	v_mfma_f32_32x32x16_f16 v[0:15], v[96:99], v[164:167], v[0:15]
	v_fma_f32 v239, v19, v71, v239
	v_max_i32_e32 v20, 0, v20
	v_max_i32_e32 v21, 0, v21
	v_fma_f32 v238, v20, v72, v238
	v_fma_f32 v239, v21, v73, v239
	v_max_i32_e32 v22, 0, v22
	v_max_i32_e32 v23, 0, v23
	v_mfma_f32_32x32x16_f16 v[0:15], v[100:103], v[160:163], v[0:15]
	v_fma_f32 v238, v22, v74, v238
	v_fma_f32 v239, v23, v75, v239
	v_max_i32_e32 v24, 0, v24
	v_max_i32_e32 v25, 0, v25
	v_fma_f32 v238, v24, v76, v238
	v_fma_f32 v239, v25, v77, v239
	v_mfma_f32_32x32x16_f16 v[0:15], v[104:107], v[156:159], v[0:15]
	v_max_i32_e32 v26, 0, v26
	v_max_i32_e32 v27, 0, v27
	v_fma_f32 v238, v26, v78, v238
	v_fma_f32 v239, v27, v79, v239
	v_max_i32_e32 v28, 0, v28
	v_max_i32_e32 v29, 0, v29
	v_mfma_f32_32x32x16_f16 v[0:15], v[108:111], v[152:155], v[0:15]
	v_fma_f32 v238, v28, v80, v238
	v_fma_f32 v239, v29, v81, v239
	v_max_i32_e32 v30, 0, v30
	v_max_i32_e32 v31, 0, v31
	v_fma_f32 v238, v30, v82, v238
	v_fma_f32 v239, v31, v83, v239
	v_mfma_f32_32x32x16_f16 v[0:15], v[112:115], v[148:151], v[0:15]
	v_add_f32_e32 v240, v238, v239
	v_mov_b32_e32 v241, v240
	v_lshlrev_b32_e32 v242, 2, v32
	s_nop 0
	v_permlane32_swap_b32_e32 v241, v240
	v_add_f32_e32 v241, v241, v240
	s_mov_b64 exec, s[4:5]
	global_store_dword v242, v241, s[6:7] offset:128
	s_mov_b64 exec, -1
	s_mov_b32 s98, 1
	s_add_i32 s24, s14, -3
	s_cmp_lt_i32 s24, s41
	s_cselect_b64 s[12:13], -1, 0
	s_cmp_ge_i32 s24, s41
	s_cbranch_scc1 .LBB0_1877
	s_waitcnt vmcnt(8)
	ds_write_b128 v209, v[140:143] offset:17408
	ds_write_b128 v209, v[144:147] offset:26112
.LBB0_1877:
	s_andn2_b64 vcc, exec, s[12:13]
	s_waitcnt lgkmcnt(0)
	s_barrier
	s_cbranch_vccnz .LBB0_1886
	s_cmp_gt_i32 s14, s41
	s_cbranch_scc1 .LBB0_1880
	v_add_co_u32_e32 v238, vcc, 0xffffe000, v34
	s_nop 1
	v_addc_co_u32_e32 v239, vcc, -1, v35, vcc
	global_load_dwordx4 v[140:143], v[238:239], off
	global_load_dwordx4 v[144:147], v[34:35], off
.LBB0_1880:
	ds_read_b128 v[250:253], v207 offset:17408
	ds_read_b128 v[210:213], v207 offset:17440
	ds_read_b128 v[214:217], v207 offset:17472
	ds_read_b128 v[218:221], v207 offset:17504
	ds_read_b128 v[222:225], v207 offset:17536
	ds_read_b128 v[226:229], v207 offset:17568
	ds_read_b128 v[230:233], v207 offset:17600
	ds_read_b128 v[234:237], v207 offset:17632
	ds_read_b128 v[176:179], v207 offset:26112
	ds_read_b128 v[172:175], v207 offset:26144
	ds_read_b128 v[168:171], v207 offset:26176
	ds_read_b128 v[164:167], v207 offset:26208
	ds_read_b128 v[160:163], v207 offset:26240
	ds_read_b128 v[156:159], v207 offset:26272
	ds_read_b128 v[152:155], v207 offset:26304
	ds_read_b128 v[148:151], v207 offset:26336
	s_cmp_eq_u32 s98, 0
	s_cbranch_scc1 .Lp11_skip5
	v_max_i32_e32 v0, 0, v0
	v_max_i32_e32 v1, 0, v1
	v_fma_f32 v243, v0, v116, 0
	v_fma_f32 v244, v1, v117, 0
	v_max_i32_e32 v2, 0, v2
	v_max_i32_e32 v3, 0, v3
	v_fma_f32 v243, v2, v118, v243
	v_fma_f32 v244, v3, v119, v244
	v_max_i32_e32 v4, 0, v4
	v_max_i32_e32 v5, 0, v5
	v_fma_f32 v243, v4, v120, v243
	v_fma_f32 v244, v5, v121, v244
	v_max_i32_e32 v6, 0, v6
	v_max_i32_e32 v7, 0, v7
	v_fma_f32 v243, v6, v122, v243
	v_fma_f32 v244, v7, v123, v244
	v_max_i32_e32 v8, 0, v8
	v_max_i32_e32 v9, 0, v9
	v_fma_f32 v243, v8, v124, v243
	v_fma_f32 v244, v9, v125, v244
	v_max_i32_e32 v10, 0, v10
	v_max_i32_e32 v11, 0, v11
	v_fma_f32 v243, v10, v126, v243
	v_fma_f32 v244, v11, v127, v244
	v_max_i32_e32 v12, 0, v12
	v_max_i32_e32 v13, 0, v13
	v_fma_f32 v243, v12, v128, v243
	v_fma_f32 v244, v13, v129, v244
	v_max_i32_e32 v14, 0, v14
	v_max_i32_e32 v15, 0, v15
	v_fma_f32 v243, v14, v130, v243
	v_fma_f32 v244, v15, v131, v244
	v_add_f32_e32 v245, v243, v244
	v_mov_b32_e32 v246, v245
	v_lshlrev_b32_e32 v247, 2, v32
	s_nop 0
	v_permlane32_swap_b32_e32 v246, v245
	v_add_f32_e32 v246, v246, v245
	s_mov_b64 exec, s[4:5]
	global_store_dword v247, v246, s[8:9] offset:128
	s_mov_b64 exec, -1
; #define LAS __attribute__((address_space(3)))
; DI void indexer_tile(const LAS unsigned char* buf, const f16x8 (&af)[2][8], const f32x4 (&wv)[2][4], float* sc0, float* sc1, int kt, int r32, int h2) {
;     ...
;     f16x8 bfr[2][8];
; #pragma unroll
;     for (int sub = 0; sub < 2; ++sub)
; #pragma unroll
;         for (int ks = 0; ks < 8; ++ks) bfr[sub][ks] = *(const LAS f16x8*)(buf + (32 * sub + r32) * KT_ROWB + (16 * ks + 8 * h2) * 2);
;     __builtin_amdgcn_sched_barrier(0);
; #pragma unroll
;     for (int sub = 0; sub < 2; ++sub) {
;         f32x16 c0, c1;
; #pragma unroll
;         for (int i = 0; i < 16; ++i) { c0[i] = 0.f; c1[i] = 0.f; }
; #pragma unroll
;         for (int ks = 0; ks < 8; ++ks) { c0 = __builtin_amdgcn_mfma_f32_32x32x16_f16(af[0][ks], bfr[sub][ks], c0, 0, 0, 0); c1 = __builtin_amdgcn_mfma_f32_32x32x16_f16(af[1][ks], bfr[sub][ks], c1, 0, 0, 0); }
;         f32x2_t a0 = {0.f, 0.f}, a1 = {0.f, 0.f};
; #pragma unroll
;         for (int q = 0; q < 4; ++q)
; #pragma unroll
;             for (int e = 0; e < 4; e += 2) {
;                 const f32x2_t r0 = {relu1(c0[4 * q + e]), relu1(c0[4 * q + e + 1])};
;                 const f32x2_t r1 = {relu1(c1[4 * q + e]), relu1(c1[4 * q + e + 1])};
;                 const f32x2_t w0 = {wv[0][q][e], wv[0][q][e + 1]}, w1 = {wv[1][q][e], wv[1][q][e + 1]};
;                 a0 = __builtin_elementwise_fma(r0, w0, a0); a1 = __builtin_elementwise_fma(r1, w1, a1); }
;         float s0 = a0.x + a0.y, s1 = a1.x + a1.y;
;         s0 += __shfl_xor(s0, 32); s1 += __shfl_xor(s1, 32);
;         if (h2 == 0) { sc0[kt * 64 + 32 * sub + r32] = s0; sc1[kt * 64 + 32 * sub + r32] = s1; }
;     }
; DI void indexer_phase(const unsigned short* QI, const unsigned short* KI16, const float* WI, float* SC, LAS unsigned char* lds, int tid, int bid, int G) {
;     ...
;                 if (kt + 3 < nt) { const unsigned short* p = src + (size_t)(kt + 3) * 64 * 128; b0 = *(const u32x4*)p; b1 = *(const u32x4*)(p + 32 * 128); }
;                 indexer_tile(buf1, af, wv, sc0, sc1, kt + 1, r32, h2);
;                 if (kt + 2 < nt) { *(LAS u32x4*)(buf0 + key0 * KT_ROWB + ch * 16) = a0; *(LAS u32x4*)(buf0 + (key0 + 32) * KT_ROWB + ch * 16) = a1; }
;                 __syncthreads();
.Lp11_skip5:
	s_waitcnt lgkmcnt(15)
	v_mfma_f32_32x32x16_f16 v[16:31], v[36:39], v[250:253], 0
	s_waitcnt lgkmcnt(14)
	v_mfma_f32_32x32x16_f16 v[16:31], v[40:43], v[210:213], v[16:31]
	s_waitcnt lgkmcnt(13)
	v_mfma_f32_32x32x16_f16 v[16:31], v[44:47], v[214:217], v[16:31]
	s_waitcnt lgkmcnt(12)
	v_mfma_f32_32x32x16_f16 v[16:31], v[48:51], v[218:221], v[16:31]
	s_waitcnt lgkmcnt(11)
	v_mfma_f32_32x32x16_f16 v[16:31], v[52:55], v[222:225], v[16:31]
	s_waitcnt lgkmcnt(10)
	v_mfma_f32_32x32x16_f16 v[16:31], v[56:59], v[226:229], v[16:31]
	s_waitcnt lgkmcnt(9)
	v_mfma_f32_32x32x16_f16 v[16:31], v[60:63], v[230:233], v[16:31]
	s_waitcnt lgkmcnt(8)
	v_mfma_f32_32x32x16_f16 v[16:31], v[64:67], v[234:237], v[16:31]
	v_mfma_f32_32x32x16_f16 v[0:15], v[84:87], v[250:253], 0
	v_mfma_f32_32x32x16_f16 v[0:15], v[88:91], v[210:213], v[0:15]
	v_mfma_f32_32x32x16_f16 v[0:15], v[92:95], v[214:217], v[0:15]
	s_nop 8
	v_max_i32_e32 v16, 0, v16
	v_max_i32_e32 v17, 0, v17
	v_fma_f32 v238, v16, v68, 0
	v_fma_f32 v239, v17, v69, 0
	v_max_i32_e32 v18, 0, v18
	v_max_i32_e32 v19, 0, v19
	v_fma_f32 v238, v18, v70, v238
	v_mfma_f32_32x32x16_f16 v[0:15], v[96:99], v[218:221], v[0:15]
	v_fma_f32 v239, v19, v71, v239
	v_max_i32_e32 v20, 0, v20
	v_max_i32_e32 v21, 0, v21
	v_fma_f32 v238, v20, v72, v238
	v_fma_f32 v239, v21, v73, v239
	v_max_i32_e32 v22, 0, v22
	v_max_i32_e32 v23, 0, v23
	v_mfma_f32_32x32x16_f16 v[0:15], v[100:103], v[222:225], v[0:15]
	v_fma_f32 v238, v22, v74, v238
	v_fma_f32 v239, v23, v75, v239
	v_max_i32_e32 v24, 0, v24
	v_max_i32_e32 v25, 0, v25
	v_fma_f32 v238, v24, v76, v238
	v_fma_f32 v239, v25, v77, v239
	v_mfma_f32_32x32x16_f16 v[0:15], v[104:107], v[226:229], v[0:15]
	v_max_i32_e32 v26, 0, v26
	v_max_i32_e32 v27, 0, v27
	v_fma_f32 v238, v26, v78, v238
	v_fma_f32 v239, v27, v79, v239
	v_max_i32_e32 v28, 0, v28
	v_max_i32_e32 v29, 0, v29
	v_mfma_f32_32x32x16_f16 v[0:15], v[108:111], v[230:233], v[0:15]
	v_fma_f32 v238, v28, v80, v238
	v_fma_f32 v239, v29, v81, v239
	v_max_i32_e32 v30, 0, v30
	v_max_i32_e32 v31, 0, v31
	v_fma_f32 v238, v30, v82, v238
	v_fma_f32 v239, v31, v83, v239
	v_mfma_f32_32x32x16_f16 v[0:15], v[112:115], v[234:237], v[0:15]
	v_add_f32_e32 v240, v238, v239
	v_mov_b32_e32 v241, v240
	v_lshlrev_b32_e32 v242, 2, v32
	s_nop 0
	v_permlane32_swap_b32_e32 v241, v240
	v_add_f32_e32 v241, v241, v240
	s_mov_b64 exec, s[4:5]
	global_store_dword v242, v241, s[6:7] offset:256
	s_mov_b64 exec, -1
	s_waitcnt lgkmcnt(0)
	v_mfma_f32_32x32x16_f16 v[16:31], v[36:39], v[176:179], 0
	v_mfma_f32_32x32x16_f16 v[16:31], v[40:43], v[172:175], v[16:31]
	v_mfma_f32_32x32x16_f16 v[16:31], v[44:47], v[168:171], v[16:31]
	s_nop 8
	v_max_i32_e32 v0, 0, v0
	v_max_i32_e32 v1, 0, v1
	v_fma_f32 v243, v0, v116, 0
	v_fma_f32 v244, v1, v117, 0
	v_max_i32_e32 v2, 0, v2
	v_max_i32_e32 v3, 0, v3
	v_fma_f32 v243, v2, v118, v243
	v_mfma_f32_32x32x16_f16 v[16:31], v[48:51], v[164:167], v[16:31]
	v_fma_f32 v244, v3, v119, v244
	v_max_i32_e32 v4, 0, v4
	v_max_i32_e32 v5, 0, v5
	v_fma_f32 v243, v4, v120, v243
	v_fma_f32 v244, v5, v121, v244
	v_max_i32_e32 v6, 0, v6
	v_max_i32_e32 v7, 0, v7
	v_mfma_f32_32x32x16_f16 v[16:31], v[52:55], v[160:163], v[16:31]
	v_fma_f32 v243, v6, v122, v243
	v_fma_f32 v244, v7, v123, v244
	v_max_i32_e32 v8, 0, v8
	v_max_i32_e32 v9, 0, v9
	v_fma_f32 v243, v8, v124, v243
	v_fma_f32 v244, v9, v125, v244
	v_mfma_f32_32x32x16_f16 v[16:31], v[56:59], v[156:159], v[16:31]
	v_max_i32_e32 v10, 0, v10
	v_max_i32_e32 v11, 0, v11
	v_fma_f32 v243, v10, v126, v243
	v_fma_f32 v244, v11, v127, v244
	v_max_i32_e32 v12, 0, v12
	v_max_i32_e32 v13, 0, v13
	v_mfma_f32_32x32x16_f16 v[16:31], v[60:63], v[152:155], v[16:31]
	v_fma_f32 v243, v12, v128, v243
	v_fma_f32 v244, v13, v129, v244
	v_max_i32_e32 v14, 0, v14
	v_max_i32_e32 v15, 0, v15
	v_fma_f32 v243, v14, v130, v243
	v_fma_f32 v244, v15, v131, v244
	v_mfma_f32_32x32x16_f16 v[16:31], v[64:67], v[148:151], v[16:31]
	v_add_f32_e32 v245, v243, v244
	v_mov_b32_e32 v246, v245
	v_lshlrev_b32_e32 v247, 2, v32
	s_nop 0
	v_permlane32_swap_b32_e32 v246, v245
	v_add_f32_e32 v246, v246, v245
	s_mov_b64 exec, s[4:5]
	global_store_dword v247, v246, s[8:9] offset:256
	s_mov_b64 exec, -1
	v_mfma_f32_32x32x16_f16 v[0:15], v[84:87], v[176:179], 0
	v_mfma_f32_32x32x16_f16 v[0:15], v[88:91], v[172:175], v[0:15]
	v_mfma_f32_32x32x16_f16 v[0:15], v[92:95], v[168:171], v[0:15]
	s_nop 8
	v_max_i32_e32 v16, 0, v16
	v_max_i32_e32 v17, 0, v17
	v_fma_f32 v238, v16, v68, 0
	v_fma_f32 v239, v17, v69, 0
	v_max_i32_e32 v18, 0, v18
	v_max_i32_e32 v19, 0, v19
	v_fma_f32 v238, v18, v70, v238
	v_mfma_f32_32x32x16_f16 v[0:15], v[96:99], v[164:167], v[0:15]
	v_fma_f32 v239, v19, v71, v239
	v_max_i32_e32 v20, 0, v20
	v_max_i32_e32 v21, 0, v21
	v_fma_f32 v238, v20, v72, v238
	v_fma_f32 v239, v21, v73, v239
	v_max_i32_e32 v22, 0, v22
	v_max_i32_e32 v23, 0, v23
	v_mfma_f32_32x32x16_f16 v[0:15], v[100:103], v[160:163], v[0:15]
	v_fma_f32 v238, v22, v74, v238
	v_fma_f32 v239, v23, v75, v239
	v_max_i32_e32 v24, 0, v24
	v_max_i32_e32 v25, 0, v25
	v_fma_f32 v238, v24, v76, v238
	v_fma_f32 v239, v25, v77, v239
	v_mfma_f32_32x32x16_f16 v[0:15], v[104:107], v[156:159], v[0:15]
	v_max_i32_e32 v26, 0, v26
	v_max_i32_e32 v27, 0, v27
	v_fma_f32 v238, v26, v78, v238
	v_fma_f32 v239, v27, v79, v239
	v_max_i32_e32 v28, 0, v28
	v_max_i32_e32 v29, 0, v29
	v_mfma_f32_32x32x16_f16 v[0:15], v[108:111], v[152:155], v[0:15]
	v_fma_f32 v238, v28, v80, v238
	v_fma_f32 v239, v29, v81, v239
	v_max_i32_e32 v30, 0, v30
	v_max_i32_e32 v31, 0, v31
	v_fma_f32 v238, v30, v82, v238
	v_fma_f32 v239, v31, v83, v239
	v_mfma_f32_32x32x16_f16 v[0:15], v[112:115], v[148:151], v[0:15]
	v_add_f32_e32 v240, v238, v239
	v_mov_b32_e32 v241, v240
	v_lshlrev_b32_e32 v242, 2, v32
	s_nop 0
	v_permlane32_swap_b32_e32 v241, v240
	v_add_f32_e32 v241, v241, v240
	s_mov_b64 exec, s[4:5]
	global_store_dword v242, v241, s[6:7] offset:384
	s_mov_b64 exec, -1
	s_mov_b32 s98, 1
	s_andn2_b64 vcc, exec, s[10:11]
	s_cbranch_vccnz .LBB0_1868
	s_waitcnt vmcnt(7)
	ds_write_b128 v209, v[132:135]
	ds_write_b128 v209, v[136:139] offset:8704
	s_branch .LBB0_1868
; #define LAS __attribute__((address_space(3)))
; DI size_t sc_row_off(int b, int s) { const int qb = s >> 7; return ((size_t)(b * 2080 + ((qb * (qb + 1)) >> 1))) * 16384 + (size_t)(s & 127) * ((qb + 1) * 128); }
; DI void indexer_tile(const LAS unsigned char* buf, const f16x8 (&af)[2][8], const f32x4 (&wv)[2][4], float* sc0, float* sc1, int kt, int r32, int h2) {
;     ...
;                 const f32x2_t r0 = {relu1(c0[4 * q + e]), relu1(c0[4 * q + e + 1])};
;                 const f32x2_t r1 = {relu1(c1[4 * q + e]), relu1(c1[4 * q + e + 1])};
;                 const f32x2_t w0 = {wv[0][q][e], wv[0][q][e + 1]}, w1 = {wv[1][q][e], wv[1][q][e + 1]};
;                 a0 = __builtin_elementwise_fma(r0, w0, a0); a1 = __builtin_elementwise_fma(r1, w1, a1); }
;         float s0 = a0.x + a0.y, s1 = a1.x + a1.y;
;         s0 += __shfl_xor(s0, 32); s1 += __shfl_xor(s1, 32);
;         if (h2 == 0) { sc0[kt * 64 + 32 * sub + r32] = s0; sc1[kt * 64 + 32 * sub + r32] = s1; }
; DI void indexer_phase(const unsigned short* QI, const unsigned short* KI16, const float* WI, float* SC, LAS unsigned char* lds, int tid, int bid, int G) {
;     ...
;             f16x8 af[2][8]; f32x4 wv[2][4];
; #pragma unroll
;             for (int tq = 0; tq < 2; ++tq) { const size_t tg = (size_t)b * SEQ + tb + 2 * w + tq;
; #pragma unroll
;                 for (int ks = 0; ks < 8; ++ks) af[tq][ks] = *(const f16x8*)(QI + tg * 4096 + r32 * 128 + 16 * ks + 8 * h2);
; #pragma unroll
;                 for (int q = 0; q < 4; ++q) wv[tq][q] = *(const f32x4*)(WI + tg * 32 + 8 * q + 4 * h2); }
;             float* sc0 = SC + sc_row_off(b, tb + 2 * w); float* sc1 = SC + sc_row_off(b, tb + 2 * w + 1);
;             const unsigned short* src = KI16 + (size_t)b * SEQ * 128 + (size_t)key0 * 128 + ch * 8;
;             u32x4 a0, a1, b0 = {0u, 0u, 0u, 0u}, b1 = {0u, 0u, 0u, 0u};
;             a0 = *(const u32x4*)src; a1 = *(const u32x4*)(src + 32 * 128);
;             if (nt > 1) { b0 = *(const u32x4*)(src + 64 * 128); b1 = *(const u32x4*)(src + 96 * 128); }
;             __syncthreads();
;             *(LAS u32x4*)(buf0 + key0 * KT_ROWB + ch * 16) = a0; *(LAS u32x4*)(buf0 + (key0 + 32) * KT_ROWB + ch * 16) = a1;
;             __syncthreads();
.LBB0_1886:
	v_max_i32_e32 v0, 0, v0
	v_max_i32_e32 v1, 0, v1
	v_fma_f32 v243, v0, v116, 0
	v_fma_f32 v244, v1, v117, 0
	v_max_i32_e32 v2, 0, v2
	v_max_i32_e32 v3, 0, v3
	v_fma_f32 v243, v2, v118, v243
	v_fma_f32 v244, v3, v119, v244
	v_max_i32_e32 v4, 0, v4
	v_max_i32_e32 v5, 0, v5
	v_fma_f32 v243, v4, v120, v243
	v_fma_f32 v244, v5, v121, v244
	v_max_i32_e32 v6, 0, v6
	v_max_i32_e32 v7, 0, v7
	v_fma_f32 v243, v6, v122, v243
	v_fma_f32 v244, v7, v123, v244
	v_max_i32_e32 v8, 0, v8
	v_max_i32_e32 v9, 0, v9
	v_fma_f32 v243, v8, v124, v243
	v_fma_f32 v244, v9, v125, v244
	v_max_i32_e32 v10, 0, v10
	v_max_i32_e32 v11, 0, v11
	v_fma_f32 v243, v10, v126, v243
	v_fma_f32 v244, v11, v127, v244
	v_max_i32_e32 v12, 0, v12
	v_max_i32_e32 v13, 0, v13
	v_fma_f32 v243, v12, v128, v243
	v_fma_f32 v244, v13, v129, v244
	v_max_i32_e32 v14, 0, v14
	v_max_i32_e32 v15, 0, v15
	v_fma_f32 v243, v14, v130, v243
	v_fma_f32 v244, v15, v131, v244
	v_add_f32_e32 v245, v243, v244
	v_mov_b32_e32 v246, v245
	v_lshlrev_b32_e32 v247, 2, v32
	s_nop 0
	v_permlane32_swap_b32_e32 v246, v245
	v_add_f32_e32 v246, v246, v245
	s_mov_b64 exec, s[4:5]
	global_store_dword v247, v246, s[8:9] offset:128
	s_mov_b64 exec, -1
	s_mov_b32 s98, 0
	s_cbranch_execz .LBB0_1869
.LBB0_1887:
	s_add_u32 s6, s38, s45
	s_addc_u32 s7, s39, 0
	s_lshl_b64 s[8:9], s[6:7], 13
	v_lshl_add_u64 v[0:1], v[180:181], 0, s[8:9]
	s_lshl_b64 s[8:9], s[6:7], 7
	s_or_b32 s6, s6, 1
	global_load_dwordx4 v[34:37], v[0:1], off
	global_load_dwordx4 v[38:41], v[0:1], off offset:32
	global_load_dwordx4 v[42:45], v[0:1], off offset:64
	global_load_dwordx4 v[46:49], v[0:1], off offset:96
	global_load_dwordx4 v[50:53], v[0:1], off offset:128
	global_load_dwordx4 v[54:57], v[0:1], off offset:160
	global_load_dwordx4 v[58:61], v[0:1], off offset:192
	global_load_dwordx4 v[62:65], v[0:1], off offset:224
	v_lshl_add_u64 v[0:1], v[182:183], 0, s[8:9]
	s_lshl_b64 s[8:9], s[6:7], 13
	global_load_dwordx4 v[66:69], v[0:1], off
	global_load_dwordx4 v[70:73], v[0:1], off offset:32
	global_load_dwordx4 v[74:77], v[0:1], off offset:64
	global_load_dwordx4 v[78:81], v[0:1], off offset:96
	v_lshl_add_u64 v[0:1], v[180:181], 0, s[8:9]
	global_load_dwordx4 v[82:85], v[0:1], off
	global_load_dwordx4 v[86:89], v[0:1], off offset:32
	global_load_dwordx4 v[90:93], v[0:1], off offset:64
	global_load_dwordx4 v[94:97], v[0:1], off offset:96
	global_load_dwordx4 v[98:101], v[0:1], off offset:128
	global_load_dwordx4 v[102:105], v[0:1], off offset:160
	global_load_dwordx4 v[106:109], v[0:1], off offset:192
	global_load_dwordx4 v[110:113], v[0:1], off offset:224
	s_lshl_b64 s[6:7], s[6:7], 7
	v_lshl_add_u64 v[0:1], v[182:183], 0, s[6:7]
	global_load_dwordx4 v[130:133], v[192:193], off
	global_load_dwordx4 v[138:141], v[194:195], off
	global_load_dwordx4 v[114:117], v[0:1], off
	global_load_dwordx4 v[118:121], v[0:1], off offset:32
	global_load_dwordx4 v[134:137], v[198:199], off
	global_load_dwordx4 v[142:145], v[196:197], off
	global_load_dwordx4 v[122:125], v[0:1], off offset:64
	global_load_dwordx4 v[126:129], v[0:1], off offset:96
	s_lshl_b64 s[6:7], s[18:19], 16
	s_add_u32 s6, s17, s6
	s_addc_u32 s7, s33, s7
	s_add_u32 s8, s6, 0x8200000
	s_addc_u32 s9, s7, 0
	s_add_u32 s6, s8, s20
	s_addc_u32 s7, s9, s21
	s_add_u32 s8, s8, s22
	s_addc_u32 s9, s9, s23
	s_mov_b32 s14, 3
	v_mov_b32_e32 v32, v206
	v_mov_b64_e32 v[178:179], v[202:203]
	s_barrier
	s_waitcnt vmcnt(7)
	ds_write_b128 v209, v[130:133]
	s_waitcnt vmcnt(0)
	ds_write_b128 v209, v[138:141] offset:8704
	s_waitcnt lgkmcnt(0)
	s_barrier
	s_mov_b32 s98, 0
	s_branch .LBB0_1889
.Lp11_fb3:
	v_max_i32_e32 v0, 0, v0
	v_max_i32_e32 v1, 0, v1
	v_fma_f32 v243, v0, v114, 0
	v_fma_f32 v244, v1, v115, 0
	v_max_i32_e32 v2, 0, v2
	v_max_i32_e32 v3, 0, v3
	v_fma_f32 v243, v2, v116, v243
	v_fma_f32 v244, v3, v117, v244
	v_max_i32_e32 v4, 0, v4
	v_max_i32_e32 v5, 0, v5
	v_fma_f32 v243, v4, v118, v243
	v_fma_f32 v244, v5, v119, v244
	v_max_i32_e32 v6, 0, v6
	v_max_i32_e32 v7, 0, v7
	v_fma_f32 v243, v6, v120, v243
	v_fma_f32 v244, v7, v121, v244
	v_max_i32_e32 v8, 0, v8
	v_max_i32_e32 v9, 0, v9
	v_fma_f32 v243, v8, v122, v243
	v_fma_f32 v244, v9, v123, v244
	v_max_i32_e32 v10, 0, v10
	v_max_i32_e32 v11, 0, v11
	v_fma_f32 v243, v10, v124, v243
	v_fma_f32 v244, v11, v125, v244
	v_max_i32_e32 v12, 0, v12
	v_max_i32_e32 v13, 0, v13
	v_fma_f32 v243, v12, v126, v243
	v_fma_f32 v244, v13, v127, v244
	v_max_i32_e32 v14, 0, v14
	v_max_i32_e32 v15, 0, v15
	v_fma_f32 v243, v14, v128, v243
	v_fma_f32 v244, v15, v129, v244
	v_add_f32_e32 v245, v243, v244
	v_mov_b32_e32 v246, v245
	v_lshlrev_b32_e32 v247, 2, v32
	s_nop 0
	v_permlane32_swap_b32_e32 v246, v245
	v_add_f32_e32 v246, v246, v245
	s_mov_b64 exec, s[4:5]
	global_store_dword v247, v246, s[8:9] offset:-128
	s_mov_b64 exec, -1
	s_mov_b32 s98, 0
	s_branch .LBB0_1818

; #define LAS __attribute__((address_space(3)))
; DI void indexer_tile(const LAS unsigned char* buf, const f16x8 (&af)[2][8], const f32x4 (&wv)[2][4], float* sc0, float* sc1, int kt, int r32, int h2) {
;     ...
;     f16x8 bfr[2][8];
; #pragma unroll
;     for (int sub = 0; sub < 2; ++sub)
; #pragma unroll
;         for (int ks = 0; ks < 8; ++ks) bfr[sub][ks] = *(const LAS f16x8*)(buf + (32 * sub + r32) * KT_ROWB + (16 * ks + 8 * h2) * 2);
;     __builtin_amdgcn_sched_barrier(0);
; #pragma unroll
;     for (int sub = 0; sub < 2; ++sub) {
;         f32x16 c0, c1;
; #pragma unroll
;         for (int i = 0; i < 16; ++i) { c0[i] = 0.f; c1[i] = 0.f; }
; #pragma unroll
;         for (int ks = 0; ks < 8; ++ks) { c0 = __builtin_amdgcn_mfma_f32_32x32x16_f16(af[0][ks], bfr[sub][ks], c0, 0, 0, 0); c1 = __builtin_amdgcn_mfma_f32_32x32x16_f16(af[1][ks], bfr[sub][ks], c1, 0, 0, 0); }
;         f32x2_t a0 = {0.f, 0.f}, a1 = {0.f, 0.f};
; #pragma unroll
;         for (int q = 0; q < 4; ++q)
; #pragma unroll
;             for (int e = 0; e < 4; e += 2) {
;                 const f32x2_t r0 = {relu1(c0[4 * q + e]), relu1(c0[4 * q + e + 1])};
;                 const f32x2_t r1 = {relu1(c1[4 * q + e]), relu1(c1[4 * q + e + 1])};
;                 const f32x2_t w0 = {wv[0][q][e], wv[0][q][e + 1]}, w1 = {wv[1][q][e], wv[1][q][e + 1]};
;                 a0 = __builtin_elementwise_fma(r0, w0, a0); a1 = __builtin_elementwise_fma(r1, w1, a1); }
;         float s0 = a0.x + a0.y, s1 = a1.x + a1.y;
;         s0 += __shfl_xor(s0, 32); s1 += __shfl_xor(s1, 32);
;         if (h2 == 0) { sc0[kt * 64 + 32 * sub + r32] = s0; sc1[kt * 64 + 32 * sub + r32] = s1; }
;     }
; DI void indexer_phase(const unsigned short* QI, const unsigned short* KI16, const float* WI, float* SC, LAS unsigned char* lds, int tid, int bid, int G) {
;     ...
;             for (int kt = 0; kt < nt; kt += 2) {
;                 if (kt + 2 < nt) { const unsigned short* p = src + (size_t)(kt + 2) * 64 * 128; a0 = *(const u32x4*)p; a1 = *(const u32x4*)(p + 32 * 128); }
;                 indexer_tile(buf0, af, wv, sc0, sc1, kt, r32, h2);
.LBB0_1889:
	s_add_i32 s15, s14, -1
	s_cmp_le_u32 s15, s42
	s_cselect_b64 s[10:11], -1, 0
	s_cmp_gt_u32 s15, s42
	s_cbranch_scc1 .LBB0_1891
	v_add_co_u32_e32 v238, vcc, 0xffffa000, v178
	s_nop 1
	v_addc_co_u32_e32 v239, vcc, -1, v179, vcc
	v_add_co_u32_e32 v240, vcc, 0xffffc000, v178
	s_nop 1
	v_addc_co_u32_e32 v241, vcc, -1, v179, vcc
	global_load_dwordx4 v[130:133], v[238:239], off
	global_load_dwordx4 v[138:141], v[240:241], off
.LBB0_1891:
	ds_read_b128 v[250:253], v207
	ds_read_b128 v[210:213], v207 offset:32
	ds_read_b128 v[214:217], v207 offset:64
	ds_read_b128 v[218:221], v207 offset:96
	ds_read_b128 v[222:225], v207 offset:128
	ds_read_b128 v[226:229], v207 offset:160
	ds_read_b128 v[230:233], v207 offset:192
	ds_read_b128 v[234:237], v207 offset:224
	ds_read_b128 v[174:177], v207 offset:8704
	ds_read_b128 v[170:173], v207 offset:8736
	ds_read_b128 v[166:169], v207 offset:8768
	ds_read_b128 v[162:165], v207 offset:8800
	ds_read_b128 v[158:161], v207 offset:8832
	ds_read_b128 v[154:157], v207 offset:8864
	ds_read_b128 v[150:153], v207 offset:8896
	ds_read_b128 v[146:149], v207 offset:8928
	s_cmp_eq_u32 s98, 0
	s_cbranch_scc1 .Lp11_skip6
	v_max_i32_e32 v0, 0, v0
	v_max_i32_e32 v1, 0, v1
	v_fma_f32 v243, v0, v114, 0
	v_fma_f32 v244, v1, v115, 0
	v_max_i32_e32 v2, 0, v2
	v_max_i32_e32 v3, 0, v3
	v_fma_f32 v243, v2, v116, v243
	v_fma_f32 v244, v3, v117, v244
	v_max_i32_e32 v4, 0, v4
	v_max_i32_e32 v5, 0, v5
	v_fma_f32 v243, v4, v118, v243
	v_fma_f32 v244, v5, v119, v244
	v_max_i32_e32 v6, 0, v6
	v_max_i32_e32 v7, 0, v7
	v_fma_f32 v243, v6, v120, v243
	v_fma_f32 v244, v7, v121, v244
	v_max_i32_e32 v8, 0, v8
	v_max_i32_e32 v9, 0, v9
	v_fma_f32 v243, v8, v122, v243
	v_fma_f32 v244, v9, v123, v244
	v_max_i32_e32 v10, 0, v10
	v_max_i32_e32 v11, 0, v11
	v_fma_f32 v243, v10, v124, v243
	v_fma_f32 v244, v11, v125, v244
	v_max_i32_e32 v12, 0, v12
	v_max_i32_e32 v13, 0, v13
	v_fma_f32 v243, v12, v126, v243
	v_fma_f32 v244, v13, v127, v244
	v_max_i32_e32 v14, 0, v14
	v_max_i32_e32 v15, 0, v15
	v_fma_f32 v243, v14, v128, v243
	v_fma_f32 v244, v15, v129, v244
	v_add_f32_e32 v245, v243, v244
	v_mov_b32_e32 v246, v245
	v_lshlrev_b32_e32 v247, 2, v32
	s_nop 0
	v_permlane32_swap_b32_e32 v246, v245
	v_add_f32_e32 v246, v246, v245
	s_mov_b64 exec, s[4:5]
	global_store_dword v247, v246, s[8:9] offset:-128
	s_mov_b64 exec, -1
.Lp11_skip6:
	s_waitcnt lgkmcnt(15)
	v_mfma_f32_32x32x16_f16 v[16:31], v[34:37], v[250:253], 0
	s_waitcnt lgkmcnt(14)
	v_mfma_f32_32x32x16_f16 v[16:31], v[38:41], v[210:213], v[16:31]
	s_waitcnt lgkmcnt(13)
	v_mfma_f32_32x32x16_f16 v[16:31], v[42:45], v[214:217], v[16:31]
	s_waitcnt lgkmcnt(12)
	v_mfma_f32_32x32x16_f16 v[16:31], v[46:49], v[218:221], v[16:31]
	s_waitcnt lgkmcnt(11)
	v_mfma_f32_32x32x16_f16 v[16:31], v[50:53], v[222:225], v[16:31]
	s_waitcnt lgkmcnt(10)
	v_mfma_f32_32x32x16_f16 v[16:31], v[54:57], v[226:229], v[16:31]
	s_waitcnt lgkmcnt(9)
	v_mfma_f32_32x32x16_f16 v[16:31], v[58:61], v[230:233], v[16:31]
	s_waitcnt lgkmcnt(8)
	v_mfma_f32_32x32x16_f16 v[16:31], v[62:65], v[234:237], v[16:31]
	v_mfma_f32_32x32x16_f16 v[0:15], v[82:85], v[250:253], 0
	v_mfma_f32_32x32x16_f16 v[0:15], v[86:89], v[210:213], v[0:15]
	v_mfma_f32_32x32x16_f16 v[0:15], v[90:93], v[214:217], v[0:15]
	s_nop 8
	v_max_i32_e32 v16, 0, v16
	v_max_i32_e32 v17, 0, v17
	v_fma_f32 v238, v16, v66, 0
	v_fma_f32 v239, v17, v67, 0
	v_max_i32_e32 v18, 0, v18
	v_max_i32_e32 v19, 0, v19
	v_fma_f32 v238, v18, v68, v238
	v_mfma_f32_32x32x16_f16 v[0:15], v[94:97], v[218:221], v[0:15]
	v_fma_f32 v239, v19, v69, v239
	v_max_i32_e32 v20, 0, v20
	v_max_i32_e32 v21, 0, v21
	v_fma_f32 v238, v20, v70, v238
	v_fma_f32 v239, v21, v71, v239
	v_max_i32_e32 v22, 0, v22
	v_max_i32_e32 v23, 0, v23
	v_mfma_f32_32x32x16_f16 v[0:15], v[98:101], v[222:225], v[0:15]
	v_fma_f32 v238, v22, v72, v238
	v_fma_f32 v239, v23, v73, v239
	v_max_i32_e32 v24, 0, v24
	v_max_i32_e32 v25, 0, v25
	v_fma_f32 v238, v24, v74, v238
	v_fma_f32 v239, v25, v75, v239
	v_mfma_f32_32x32x16_f16 v[0:15], v[102:105], v[226:229], v[0:15]
	v_max_i32_e32 v26, 0, v26
	v_max_i32_e32 v27, 0, v27
	v_fma_f32 v238, v26, v76, v238
	v_fma_f32 v239, v27, v77, v239
	v_max_i32_e32 v28, 0, v28
	v_max_i32_e32 v29, 0, v29
	v_mfma_f32_32x32x16_f16 v[0:15], v[106:109], v[230:233], v[0:15]
	v_fma_f32 v238, v28, v78, v238
	v_fma_f32 v239, v29, v79, v239
	v_max_i32_e32 v30, 0, v30
	v_max_i32_e32 v31, 0, v31
	v_fma_f32 v238, v30, v80, v238
	v_fma_f32 v239, v31, v81, v239
	v_mfma_f32_32x32x16_f16 v[0:15], v[110:113], v[234:237], v[0:15]
	v_add_f32_e32 v240, v238, v239
	v_mov_b32_e32 v241, v240
	v_lshlrev_b32_e32 v242, 2, v32
	s_nop 0
	v_permlane32_swap_b32_e32 v241, v240
	v_add_f32_e32 v241, v241, v240
	s_mov_b64 exec, s[4:5]
	global_store_dword v242, v241, s[6:7]
	s_mov_b64 exec, -1
	s_waitcnt lgkmcnt(0)
; #define LAS __attribute__((address_space(3)))
; DI void indexer_tile(const LAS unsigned char* buf, const f16x8 (&af)[2][8], const f32x4 (&wv)[2][4], float* sc0, float* sc1, int kt, int r32, int h2) {
;     ...
;     f16x8 bfr[2][8];
; #pragma unroll
;     for (int sub = 0; sub < 2; ++sub)
; #pragma unroll
;         for (int ks = 0; ks < 8; ++ks) bfr[sub][ks] = *(const LAS f16x8*)(buf + (32 * sub + r32) * KT_ROWB + (16 * ks + 8 * h2) * 2);
;     __builtin_amdgcn_sched_barrier(0);
; #pragma unroll
;     for (int sub = 0; sub < 2; ++sub) {
;         f32x16 c0, c1;
; #pragma unroll
;         for (int i = 0; i < 16; ++i) { c0[i] = 0.f; c1[i] = 0.f; }
; #pragma unroll
;         for (int ks = 0; ks < 8; ++ks) { c0 = __builtin_amdgcn_mfma_f32_32x32x16_f16(af[0][ks], bfr[sub][ks], c0, 0, 0, 0); c1 = __builtin_amdgcn_mfma_f32_32x32x16_f16(af[1][ks], bfr[sub][ks], c1, 0, 0, 0); }
;         f32x2_t a0 = {0.f, 0.f}, a1 = {0.f, 0.f};
; #pragma unroll
;         for (int q = 0; q < 4; ++q)
; #pragma unroll
;             for (int e = 0; e < 4; e += 2) {
;                 const f32x2_t r0 = {relu1(c0[4 * q + e]), relu1(c0[4 * q + e + 1])};
;                 const f32x2_t r1 = {relu1(c1[4 * q + e]), relu1(c1[4 * q + e + 1])};
;                 const f32x2_t w0 = {wv[0][q][e], wv[0][q][e + 1]}, w1 = {wv[1][q][e], wv[1][q][e + 1]};
;                 a0 = __builtin_elementwise_fma(r0, w0, a0); a1 = __builtin_elementwise_fma(r1, w1, a1); }
;         float s0 = a0.x + a0.y, s1 = a1.x + a1.y;
;         s0 += __shfl_xor(s0, 32); s1 += __shfl_xor(s1, 32);
;         if (h2 == 0) { sc0[kt * 64 + 32 * sub + r32] = s0; sc1[kt * 64 + 32 * sub + r32] = s1; }
;     }
; DI void indexer_phase(const unsigned short* QI, const unsigned short* KI16, const float* WI, float* SC, LAS unsigned char* lds, int tid, int bid, int G) {
;     ...
;                 indexer_tile(buf0, af, wv, sc0, sc1, kt, r32, h2);
;                 if (kt + 1 < nt) { *(LAS u32x4*)(buf1 + key0 * KT_ROWB + ch * 16) = b0; *(LAS u32x4*)(buf1 + (key0 + 32) * KT_ROWB + ch * 16) = b1; }
	v_mfma_f32_32x32x16_f16 v[16:31], v[34:37], v[174:177], 0
	v_mfma_f32_32x32x16_f16 v[16:31], v[38:41], v[170:173], v[16:31]
	v_mfma_f32_32x32x16_f16 v[16:31], v[42:45], v[166:169], v[16:31]
	s_nop 8
	v_max_i32_e32 v0, 0, v0
	v_max_i32_e32 v1, 0, v1
	v_fma_f32 v243, v0, v114, 0
	v_fma_f32 v244, v1, v115, 0
	v_max_i32_e32 v2, 0, v2
	v_max_i32_e32 v3, 0, v3
	v_fma_f32 v243, v2, v116, v243
	v_mfma_f32_32x32x16_f16 v[16:31], v[46:49], v[162:165], v[16:31]
	v_fma_f32 v244, v3, v117, v244
	v_max_i32_e32 v4, 0, v4
	v_max_i32_e32 v5, 0, v5
	v_fma_f32 v243, v4, v118, v243
	v_fma_f32 v244, v5, v119, v244
	v_max_i32_e32 v6, 0, v6
	v_max_i32_e32 v7, 0, v7
	v_mfma_f32_32x32x16_f16 v[16:31], v[50:53], v[158:161], v[16:31]
	v_fma_f32 v243, v6, v120, v243
	v_fma_f32 v244, v7, v121, v244
	v_max_i32_e32 v8, 0, v8
	v_max_i32_e32 v9, 0, v9
	v_fma_f32 v243, v8, v122, v243
	v_fma_f32 v244, v9, v123, v244
	v_mfma_f32_32x32x16_f16 v[16:31], v[54:57], v[154:157], v[16:31]
	v_max_i32_e32 v10, 0, v10
	v_max_i32_e32 v11, 0, v11
	v_fma_f32 v243, v10, v124, v243
	v_fma_f32 v244, v11, v125, v244
	v_max_i32_e32 v12, 0, v12
	v_max_i32_e32 v13, 0, v13
	v_mfma_f32_32x32x16_f16 v[16:31], v[58:61], v[150:153], v[16:31]
	v_fma_f32 v243, v12, v126, v243
	v_fma_f32 v244, v13, v127, v244
	v_max_i32_e32 v14, 0, v14
	v_max_i32_e32 v15, 0, v15
	v_fma_f32 v243, v14, v128, v243
	v_fma_f32 v244, v15, v129, v244
	v_mfma_f32_32x32x16_f16 v[16:31], v[62:65], v[146:149], v[16:31]
	v_add_f32_e32 v245, v243, v244
	v_mov_b32_e32 v246, v245
	v_lshlrev_b32_e32 v247, 2, v32
	s_nop 0
	v_permlane32_swap_b32_e32 v246, v245
	v_add_f32_e32 v246, v246, v245
	s_mov_b64 exec, s[4:5]
	global_store_dword v247, v246, s[8:9]
	s_mov_b64 exec, -1
	v_mfma_f32_32x32x16_f16 v[0:15], v[82:85], v[174:177], 0
	v_mfma_f32_32x32x16_f16 v[0:15], v[86:89], v[170:173], v[0:15]
	v_mfma_f32_32x32x16_f16 v[0:15], v[90:93], v[166:169], v[0:15]
	s_nop 8
	v_max_i32_e32 v16, 0, v16
	v_max_i32_e32 v17, 0, v17
	v_fma_f32 v238, v16, v66, 0
	v_fma_f32 v239, v17, v67, 0
	v_max_i32_e32 v18, 0, v18
	v_max_i32_e32 v19, 0, v19
	v_fma_f32 v238, v18, v68, v238
	v_mfma_f32_32x32x16_f16 v[0:15], v[94:97], v[162:165], v[0:15]
	v_fma_f32 v239, v19, v69, v239
	v_max_i32_e32 v20, 0, v20
	v_max_i32_e32 v21, 0, v21
	v_fma_f32 v238, v20, v70, v238
	v_fma_f32 v239, v21, v71, v239
	v_max_i32_e32 v22, 0, v22
	v_max_i32_e32 v23, 0, v23
	v_mfma_f32_32x32x16_f16 v[0:15], v[98:101], v[158:161], v[0:15]
	v_fma_f32 v238, v22, v72, v238
	v_fma_f32 v239, v23, v73, v239
	v_max_i32_e32 v24, 0, v24
	v_max_i32_e32 v25, 0, v25
	v_fma_f32 v238, v24, v74, v238
	v_fma_f32 v239, v25, v75, v239
	v_mfma_f32_32x32x16_f16 v[0:15], v[102:105], v[154:157], v[0:15]
	v_max_i32_e32 v26, 0, v26
	v_max_i32_e32 v27, 0, v27
	v_fma_f32 v238, v26, v76, v238
	v_fma_f32 v239, v27, v77, v239
	v_max_i32_e32 v28, 0, v28
	v_max_i32_e32 v29, 0, v29
	v_mfma_f32_32x32x16_f16 v[0:15], v[106:109], v[150:153], v[0:15]
	v_fma_f32 v238, v28, v78, v238
	v_fma_f32 v239, v29, v79, v239
	v_max_i32_e32 v30, 0, v30
	v_max_i32_e32 v31, 0, v31
	v_fma_f32 v238, v30, v80, v238
	v_fma_f32 v239, v31, v81, v239
	v_mfma_f32_32x32x16_f16 v[0:15], v[110:113], v[146:149], v[0:15]
	v_add_f32_e32 v240, v238, v239
	v_mov_b32_e32 v241, v240
	v_lshlrev_b32_e32 v242, 2, v32
	s_nop 0
	v_permlane32_swap_b32_e32 v241, v240
	v_add_f32_e32 v241, v241, v240
	s_mov_b64 exec, s[4:5]
	global_store_dword v242, v241, s[6:7] offset:128
	s_mov_b64 exec, -1
	s_mov_b32 s98, 1
	s_add_i32 s18, s14, -3
	s_cmp_lt_u32 s18, s42
	s_cselect_b64 s[12:13], -1, 0
	s_cmp_ge_u32 s18, s42
	s_cbranch_scc1 .LBB0_1897
	s_waitcnt vmcnt(8)
	ds_write_b128 v209, v[134:137] offset:17408
	ds_write_b128 v209, v[142:145] offset:26112
.LBB0_1897:
	s_andn2_b64 vcc, exec, s[12:13]
	s_waitcnt lgkmcnt(0)
	s_barrier
	s_cbranch_vccnz .LBB0_1906
	s_cmp_gt_u32 s14, s42
	s_cbranch_scc1 .LBB0_1900
	v_add_co_u32_e32 v238, vcc, 0xffffe000, v178
	s_nop 1
	v_addc_co_u32_e32 v239, vcc, -1, v179, vcc
	global_load_dwordx4 v[134:137], v[238:239], off
	global_load_dwordx4 v[142:145], v[178:179], off
.LBB0_1900:
	ds_read_b128 v[250:253], v207 offset:17408
	ds_read_b128 v[210:213], v207 offset:17440
	ds_read_b128 v[214:217], v207 offset:17472
	ds_read_b128 v[218:221], v207 offset:17504
	ds_read_b128 v[222:225], v207 offset:17536
	ds_read_b128 v[226:229], v207 offset:17568
	ds_read_b128 v[230:233], v207 offset:17600
	ds_read_b128 v[234:237], v207 offset:17632
	ds_read_b128 v[174:177], v207 offset:26112
	ds_read_b128 v[170:173], v207 offset:26144
	ds_read_b128 v[166:169], v207 offset:26176
	ds_read_b128 v[162:165], v207 offset:26208
	ds_read_b128 v[158:161], v207 offset:26240
	ds_read_b128 v[154:157], v207 offset:26272
	ds_read_b128 v[150:153], v207 offset:26304
	ds_read_b128 v[146:149], v207 offset:26336
	s_cmp_eq_u32 s98, 0
	s_cbranch_scc1 .Lp11_skip7
	v_max_i32_e32 v0, 0, v0
	v_max_i32_e32 v1, 0, v1
	v_fma_f32 v243, v0, v114, 0
	v_fma_f32 v244, v1, v115, 0
	v_max_i32_e32 v2, 0, v2
	v_max_i32_e32 v3, 0, v3
	v_fma_f32 v243, v2, v116, v243
	v_fma_f32 v244, v3, v117, v244
	v_max_i32_e32 v4, 0, v4
	v_max_i32_e32 v5, 0, v5
	v_fma_f32 v243, v4, v118, v243
	v_fma_f32 v244, v5, v119, v244
	v_max_i32_e32 v6, 0, v6
	v_max_i32_e32 v7, 0, v7
	v_fma_f32 v243, v6, v120, v243
	v_fma_f32 v244, v7, v121, v244
	v_max_i32_e32 v8, 0, v8
	v_max_i32_e32 v9, 0, v9
	v_fma_f32 v243, v8, v122, v243
	v_fma_f32 v244, v9, v123, v244
	v_max_i32_e32 v10, 0, v10
	v_max_i32_e32 v11, 0, v11
	v_fma_f32 v243, v10, v124, v243
	v_fma_f32 v244, v11, v125, v244
	v_max_i32_e32 v12, 0, v12
	v_max_i32_e32 v13, 0, v13
	v_fma_f32 v243, v12, v126, v243
	v_fma_f32 v244, v13, v127, v244
	v_max_i32_e32 v14, 0, v14
	v_max_i32_e32 v15, 0, v15
	v_fma_f32 v243, v14, v128, v243
	v_fma_f32 v244, v15, v129, v244
	v_add_f32_e32 v245, v243, v244
	v_mov_b32_e32 v246, v245
	v_lshlrev_b32_e32 v247, 2, v32
	s_nop 0
	v_permlane32_swap_b32_e32 v246, v245
	v_add_f32_e32 v246, v246, v245
	s_mov_b64 exec, s[4:5]
	global_store_dword v247, v246, s[8:9] offset:128
	s_mov_b64 exec, -1
; #define LAS __attribute__((address_space(3)))
; DI void indexer_tile(const LAS unsigned char* buf, const f16x8 (&af)[2][8], const f32x4 (&wv)[2][4], float* sc0, float* sc1, int kt, int r32, int h2) {
;     ...
;     f16x8 bfr[2][8];
; #pragma unroll
;     for (int sub = 0; sub < 2; ++sub)
; #pragma unroll
;         for (int ks = 0; ks < 8; ++ks) bfr[sub][ks] = *(const LAS f16x8*)(buf + (32 * sub + r32) * KT_ROWB + (16 * ks + 8 * h2) * 2);
;     __builtin_amdgcn_sched_barrier(0);
; #pragma unroll
;     for (int sub = 0; sub < 2; ++sub) {
;         f32x16 c0, c1;
; #pragma unroll
;         for (int i = 0; i < 16; ++i) { c0[i] = 0.f; c1[i] = 0.f; }
; #pragma unroll
;         for (int ks = 0; ks < 8; ++ks) { c0 = __builtin_amdgcn_mfma_f32_32x32x16_f16(af[0][ks], bfr[sub][ks], c0, 0, 0, 0); c1 = __builtin_amdgcn_mfma_f32_32x32x16_f16(af[1][ks], bfr[sub][ks], c1, 0, 0, 0); }
;         f32x2_t a0 = {0.f, 0.f}, a1 = {0.f, 0.f};
; #pragma unroll
;         for (int q = 0; q < 4; ++q)
; #pragma unroll
;             for (int e = 0; e < 4; e += 2) {
;                 const f32x2_t r0 = {relu1(c0[4 * q + e]), relu1(c0[4 * q + e + 1])};
;                 const f32x2_t r1 = {relu1(c1[4 * q + e]), relu1(c1[4 * q + e + 1])};
;                 const f32x2_t w0 = {wv[0][q][e], wv[0][q][e + 1]}, w1 = {wv[1][q][e], wv[1][q][e + 1]};
;                 a0 = __builtin_elementwise_fma(r0, w0, a0); a1 = __builtin_elementwise_fma(r1, w1, a1); }
;         float s0 = a0.x + a0.y, s1 = a1.x + a1.y;
;         s0 += __shfl_xor(s0, 32); s1 += __shfl_xor(s1, 32);
;         if (h2 == 0) { sc0[kt * 64 + 32 * sub + r32] = s0; sc1[kt * 64 + 32 * sub + r32] = s1; }
;     }
; DI void indexer_phase(const unsigned short* QI, const unsigned short* KI16, const float* WI, float* SC, LAS unsigned char* lds, int tid, int bid, int G) {
;     ...
;                 if (kt + 3 < nt) { const unsigned short* p = src + (size_t)(kt + 3) * 64 * 128; b0 = *(const u32x4*)p; b1 = *(const u32x4*)(p + 32 * 128); }
;                 indexer_tile(buf1, af, wv, sc0, sc1, kt + 1, r32, h2);
;                 if (kt + 2 < nt) { *(LAS u32x4*)(buf0 + key0 * KT_ROWB + ch * 16) = a0; *(LAS u32x4*)(buf0 + (key0 + 32) * KT_ROWB + ch * 16) = a1; }
;                 __syncthreads();
.Lp11_skip7:
	s_waitcnt lgkmcnt(15)
	v_mfma_f32_32x32x16_f16 v[16:31], v[34:37], v[250:253], 0
	s_waitcnt lgkmcnt(14)
	v_mfma_f32_32x32x16_f16 v[16:31], v[38:41], v[210:213], v[16:31]
	s_waitcnt lgkmcnt(13)
	v_mfma_f32_32x32x16_f16 v[16:31], v[42:45], v[214:217], v[16:31]
	s_waitcnt lgkmcnt(12)
	v_mfma_f32_32x32x16_f16 v[16:31], v[46:49], v[218:221], v[16:31]
	s_waitcnt lgkmcnt(11)
	v_mfma_f32_32x32x16_f16 v[16:31], v[50:53], v[222:225], v[16:31]
	s_waitcnt lgkmcnt(10)
	v_mfma_f32_32x32x16_f16 v[16:31], v[54:57], v[226:229], v[16:31]
	s_waitcnt lgkmcnt(9)
	v_mfma_f32_32x32x16_f16 v[16:31], v[58:61], v[230:233], v[16:31]
	s_waitcnt lgkmcnt(8)
	v_mfma_f32_32x32x16_f16 v[16:31], v[62:65], v[234:237], v[16:31]
	v_mfma_f32_32x32x16_f16 v[0:15], v[82:85], v[250:253], 0
	v_mfma_f32_32x32x16_f16 v[0:15], v[86:89], v[210:213], v[0:15]
	v_mfma_f32_32x32x16_f16 v[0:15], v[90:93], v[214:217], v[0:15]
	s_nop 8
	v_max_i32_e32 v16, 0, v16
	v_max_i32_e32 v17, 0, v17
	v_fma_f32 v238, v16, v66, 0
	v_fma_f32 v239, v17, v67, 0
	v_max_i32_e32 v18, 0, v18
	v_max_i32_e32 v19, 0, v19
	v_fma_f32 v238, v18, v68, v238
	v_mfma_f32_32x32x16_f16 v[0:15], v[94:97], v[218:221], v[0:15]
	v_fma_f32 v239, v19, v69, v239
	v_max_i32_e32 v20, 0, v20
	v_max_i32_e32 v21, 0, v21
	v_fma_f32 v238, v20, v70, v238
	v_fma_f32 v239, v21, v71, v239
	v_max_i32_e32 v22, 0, v22
	v_max_i32_e32 v23, 0, v23
	v_mfma_f32_32x32x16_f16 v[0:15], v[98:101], v[222:225], v[0:15]
	v_fma_f32 v238, v22, v72, v238
	v_fma_f32 v239, v23, v73, v239
	v_max_i32_e32 v24, 0, v24
	v_max_i32_e32 v25, 0, v25
	v_fma_f32 v238, v24, v74, v238
	v_fma_f32 v239, v25, v75, v239
	v_mfma_f32_32x32x16_f16 v[0:15], v[102:105], v[226:229], v[0:15]
	v_max_i32_e32 v26, 0, v26
	v_max_i32_e32 v27, 0, v27
	v_fma_f32 v238, v26, v76, v238
	v_fma_f32 v239, v27, v77, v239
	v_max_i32_e32 v28, 0, v28
	v_max_i32_e32 v29, 0, v29
	v_mfma_f32_32x32x16_f16 v[0:15], v[106:109], v[230:233], v[0:15]
	v_fma_f32 v238, v28, v78, v238
	v_fma_f32 v239, v29, v79, v239
	v_max_i32_e32 v30, 0, v30
	v_max_i32_e32 v31, 0, v31
	v_fma_f32 v238, v30, v80, v238
	v_fma_f32 v239, v31, v81, v239
	v_mfma_f32_32x32x16_f16 v[0:15], v[110:113], v[234:237], v[0:15]
	v_add_f32_e32 v240, v238, v239
	v_mov_b32_e32 v241, v240
	v_lshlrev_b32_e32 v242, 2, v32
	s_nop 0
	v_permlane32_swap_b32_e32 v241, v240
	v_add_f32_e32 v241, v241, v240
	s_mov_b64 exec, s[4:5]
	global_store_dword v242, v241, s[6:7] offset:256
	s_mov_b64 exec, -1
	s_waitcnt lgkmcnt(0)
	v_mfma_f32_32x32x16_f16 v[16:31], v[34:37], v[174:177], 0
	v_mfma_f32_32x32x16_f16 v[16:31], v[38:41], v[170:173], v[16:31]
	v_mfma_f32_32x32x16_f16 v[16:31], v[42:45], v[166:169], v[16:31]
	s_nop 8
	v_max_i32_e32 v0, 0, v0
	v_max_i32_e32 v1, 0, v1
	v_fma_f32 v243, v0, v114, 0
	v_fma_f32 v244, v1, v115, 0
	v_max_i32_e32 v2, 0, v2
	v_max_i32_e32 v3, 0, v3
	v_fma_f32 v243, v2, v116, v243
	v_mfma_f32_32x32x16_f16 v[16:31], v[46:49], v[162:165], v[16:31]
	v_fma_f32 v244, v3, v117, v244
	v_max_i32_e32 v4, 0, v4
	v_max_i32_e32 v5, 0, v5
	v_fma_f32 v243, v4, v118, v243
	v_fma_f32 v244, v5, v119, v244
	v_max_i32_e32 v6, 0, v6
	v_max_i32_e32 v7, 0, v7
	v_mfma_f32_32x32x16_f16 v[16:31], v[50:53], v[158:161], v[16:31]
	v_fma_f32 v243, v6, v120, v243
	v_fma_f32 v244, v7, v121, v244
	v_max_i32_e32 v8, 0, v8
	v_max_i32_e32 v9, 0, v9
	v_fma_f32 v243, v8, v122, v243
	v_fma_f32 v244, v9, v123, v244
	v_mfma_f32_32x32x16_f16 v[16:31], v[54:57], v[154:157], v[16:31]
	v_max_i32_e32 v10, 0, v10
	v_max_i32_e32 v11, 0, v11
	v_fma_f32 v243, v10, v124, v243
	v_fma_f32 v244, v11, v125, v244
	v_max_i32_e32 v12, 0, v12
	v_max_i32_e32 v13, 0, v13
	v_mfma_f32_32x32x16_f16 v[16:31], v[58:61], v[150:153], v[16:31]
	v_fma_f32 v243, v12, v126, v243
	v_fma_f32 v244, v13, v127, v244
	v_max_i32_e32 v14, 0, v14
	v_max_i32_e32 v15, 0, v15
	v_fma_f32 v243, v14, v128, v243
	v_fma_f32 v244, v15, v129, v244
	v_mfma_f32_32x32x16_f16 v[16:31], v[62:65], v[146:149], v[16:31]
	v_add_f32_e32 v245, v243, v244
	v_mov_b32_e32 v246, v245
	v_lshlrev_b32_e32 v247, 2, v32
	s_nop 0
	v_permlane32_swap_b32_e32 v246, v245
	v_add_f32_e32 v246, v246, v245
	s_mov_b64 exec, s[4:5]
	global_store_dword v247, v246, s[8:9] offset:256
	s_mov_b64 exec, -1
	v_mfma_f32_32x32x16_f16 v[0:15], v[82:85], v[174:177], 0
	v_mfma_f32_32x32x16_f16 v[0:15], v[86:89], v[170:173], v[0:15]
	v_mfma_f32_32x32x16_f16 v[0:15], v[90:93], v[166:169], v[0:15]
	s_nop 8
	v_max_i32_e32 v16, 0, v16
	v_max_i32_e32 v17, 0, v17
	v_fma_f32 v238, v16, v66, 0
	v_fma_f32 v239, v17, v67, 0
	v_max_i32_e32 v18, 0, v18
	v_max_i32_e32 v19, 0, v19
	v_fma_f32 v238, v18, v68, v238
	v_mfma_f32_32x32x16_f16 v[0:15], v[94:97], v[162:165], v[0:15]
	v_fma_f32 v239, v19, v69, v239
	v_max_i32_e32 v20, 0, v20
	v_max_i32_e32 v21, 0, v21
	v_fma_f32 v238, v20, v70, v238
	v_fma_f32 v239, v21, v71, v239
	v_max_i32_e32 v22, 0, v22
	v_max_i32_e32 v23, 0, v23
	v_mfma_f32_32x32x16_f16 v[0:15], v[98:101], v[158:161], v[0:15]
	v_fma_f32 v238, v22, v72, v238
	v_fma_f32 v239, v23, v73, v239
	v_max_i32_e32 v24, 0, v24
	v_max_i32_e32 v25, 0, v25
	v_fma_f32 v238, v24, v74, v238
	v_fma_f32 v239, v25, v75, v239
	v_mfma_f32_32x32x16_f16 v[0:15], v[102:105], v[154:157], v[0:15]
	v_max_i32_e32 v26, 0, v26
	v_max_i32_e32 v27, 0, v27
	v_fma_f32 v238, v26, v76, v238
	v_fma_f32 v239, v27, v77, v239
	v_max_i32_e32 v28, 0, v28
	v_max_i32_e32 v29, 0, v29
	v_mfma_f32_32x32x16_f16 v[0:15], v[106:109], v[150:153], v[0:15]
	v_fma_f32 v238, v28, v78, v238
	v_fma_f32 v239, v29, v79, v239
	v_max_i32_e32 v30, 0, v30
	v_max_i32_e32 v31, 0, v31
	v_fma_f32 v238, v30, v80, v238
	v_fma_f32 v239, v31, v81, v239
	v_mfma_f32_32x32x16_f16 v[0:15], v[110:113], v[146:149], v[0:15]
	v_add_f32_e32 v240, v238, v239
	v_mov_b32_e32 v241, v240
	v_lshlrev_b32_e32 v242, 2, v32
	s_nop 0
	v_permlane32_swap_b32_e32 v241, v240
	v_add_f32_e32 v241, v241, v240
	s_mov_b64 exec, s[4:5]
	global_store_dword v242, v241, s[6:7] offset:384
	s_mov_b64 exec, -1
	s_mov_b32 s98, 1
	s_andn2_b64 vcc, exec, s[10:11]
	s_cbranch_vccnz .LBB0_1888
	s_waitcnt vmcnt(7)
	ds_write_b128 v209, v[130:133]
	ds_write_b128 v209, v[138:141] offset:8704
	s_branch .LBB0_1888
; DI void indexer_tile(const LAS unsigned char* buf, const f16x8 (&af)[2][8], const f32x4 (&wv)[2][4], float* sc0, float* sc1, int kt, int r32, int h2) {
;     ...
;                 const f32x2_t r0 = {relu1(c0[4 * q + e]), relu1(c0[4 * q + e + 1])};
;                 const f32x2_t r1 = {relu1(c1[4 * q + e]), relu1(c1[4 * q + e + 1])};
;                 const f32x2_t w0 = {wv[0][q][e], wv[0][q][e + 1]}, w1 = {wv[1][q][e], wv[1][q][e + 1]};
;                 a0 = __builtin_elementwise_fma(r0, w0, a0); a1 = __builtin_elementwise_fma(r1, w1, a1); }
;         float s0 = a0.x + a0.y, s1 = a1.x + a1.y;
;         s0 += __shfl_xor(s0, 32); s1 += __shfl_xor(s1, 32);
;         if (h2 == 0) { sc0[kt * 64 + 32 * sub + r32] = s0; sc1[kt * 64 + 32 * sub + r32] = s1; }
; DI void indexer_phase(const unsigned short* QI, const unsigned short* KI16, const float* WI, float* SC, LAS unsigned char* lds, int tid, int bid, int G) {
;     ...
;                 __syncthreads();
;                 if (kt + 1 >= nt) break;
.LBB0_1906:
	v_max_i32_e32 v0, 0, v0
	v_max_i32_e32 v1, 0, v1
	v_fma_f32 v243, v0, v114, 0
	v_fma_f32 v244, v1, v115, 0
	v_max_i32_e32 v2, 0, v2
	v_max_i32_e32 v3, 0, v3
	v_fma_f32 v243, v2, v116, v243
	v_fma_f32 v244, v3, v117, v244
	v_max_i32_e32 v4, 0, v4
	v_max_i32_e32 v5, 0, v5
	v_fma_f32 v243, v4, v118, v243
	v_fma_f32 v244, v5, v119, v244
	v_max_i32_e32 v6, 0, v6
	v_max_i32_e32 v7, 0, v7
	v_fma_f32 v243, v6, v120, v243
	v_fma_f32 v244, v7, v121, v244
	v_max_i32_e32 v8, 0, v8
	v_max_i32_e32 v9, 0, v9
	v_fma_f32 v243, v8, v122, v243
	v_fma_f32 v244, v9, v123, v244
	v_max_i32_e32 v10, 0, v10
	v_max_i32_e32 v11, 0, v11
	v_fma_f32 v243, v10, v124, v243
	v_fma_f32 v244, v11, v125, v244
	v_max_i32_e32 v12, 0, v12
	v_max_i32_e32 v13, 0, v13
	v_fma_f32 v243, v12, v126, v243
	v_fma_f32 v244, v13, v127, v244
	v_max_i32_e32 v14, 0, v14
	v_max_i32_e32 v15, 0, v15
	v_fma_f32 v243, v14, v128, v243
	v_fma_f32 v244, v15, v129, v244
	v_add_f32_e32 v245, v243, v244
	v_mov_b32_e32 v246, v245
	v_lshlrev_b32_e32 v247, 2, v32
	s_nop 0
	v_permlane32_swap_b32_e32 v246, v245
	v_add_f32_e32 v246, v246, v245
	s_mov_b64 exec, s[4:5]
	global_store_dword v247, v246, s[8:9] offset:128
	s_mov_b64 exec, -1
	s_mov_b32 s98, 0
	s_cbranch_execz .LBB0_1889
	s_branch .LBB0_1818

; #define LAS __attribute__((address_space(3)))
; __global__ void __launch_bounds__(NTHR, 2) mk_fwd(Args args) {
;     extern __shared__ __attribute__((aligned(16))) unsigned char lds_raw[];
;     LAS unsigned char* lds = (LAS unsigned char*)lds_raw;
;     const int bid = blockIdx.x, G = gridDim.x;
;     const int wid_s = __builtin_amdgcn_readfirstlane((int)(threadIdx.x >> 6));
	.amdhsa_kernel _Z6mk_fwd4Args
		.amdhsa_group_segment_fixed_size 0
		.amdhsa_private_segment_fixed_size 0
		.amdhsa_kernarg_size 456
		.amdhsa_user_sgpr_count 2
		.amdhsa_user_sgpr_dispatch_ptr 0
		.amdhsa_user_sgpr_queue_ptr 0
		.amdhsa_user_sgpr_kernarg_segment_ptr 1
		.amdhsa_user_sgpr_dispatch_id 0
		.amdhsa_user_sgpr_kernarg_preload_length 0
		.amdhsa_user_sgpr_kernarg_preload_offset 0
		.amdhsa_user_sgpr_private_segment_size 0
		.amdhsa_uses_dynamic_stack 0
		.amdhsa_enable_private_segment 0
		.amdhsa_system_sgpr_workgroup_id_x 1
		.amdhsa_system_sgpr_workgroup_id_y 0
		.amdhsa_system_sgpr_workgroup_id_z 0
		.amdhsa_system_sgpr_workgroup_info 0
		.amdhsa_system_vgpr_workitem_id 0
		.amdhsa_next_free_vgpr 256
		.amdhsa_next_free_sgpr 102
		.amdhsa_accum_offset 256
		.amdhsa_reserve_vcc 1
		.amdhsa_float_round_mode_32 0
		.amdhsa_float_round_mode_16_64 0
		.amdhsa_float_denorm_mode_32 3
		.amdhsa_float_denorm_mode_16_64 3
		.amdhsa_dx10_clamp 1
		.amdhsa_ieee_mode 1
		.amdhsa_fp16_overflow 0
		.amdhsa_tg_split 0
		.amdhsa_exception_fp_ieee_invalid_op 0
		.amdhsa_exception_fp_denorm_src 0
		.amdhsa_exception_fp_ieee_div_zero 0
		.amdhsa_exception_fp_ieee_overflow 0
		.amdhsa_exception_fp_ieee_underflow 0
		.amdhsa_exception_fp_ieee_inexact 0
		.amdhsa_exception_int_div_zero 0
	.end_amdhsa_kernel

; __global__ void __launch_bounds__(NTHR, 2) mk_fwd(Args args) {
amdhsa.kernels:
  - .agpr_count:     0
    .args:
      - .offset:         0
        .size:           200
        .value_kind:     by_value
      - .offset:         200
        .size:           4
        .value_kind:     hidden_block_count_x
      - .offset:         204
        .size:           4
        .value_kind:     hidden_block_count_y
      - .offset:         208
        .size:           4
        .value_kind:     hidden_block_count_z
      - .offset:         212
        .size:           2
        .value_kind:     hidden_group_size_x
      - .offset:         214
        .size:           2
        .value_kind:     hidden_group_size_y
      - .offset:         216
        .size:           2
        .value_kind:     hidden_group_size_z
      - .offset:         218
        .size:           2
        .value_kind:     hidden_remainder_x
      - .offset:         220
        .size:           2
        .value_kind:     hidden_remainder_y
      - .offset:         222
        .size:           2
        .value_kind:     hidden_remainder_z
      - .offset:         240
        .size:           8
        .value_kind:     hidden_global_offset_x
      - .offset:         248
        .size:           8
        .value_kind:     hidden_global_offset_y
      - .offset:         256
        .size:           8
        .value_kind:     hidden_global_offset_z
      - .offset:         264
        .size:           2
        .value_kind:     hidden_grid_dims
      - .offset:         320
        .size:           4
        .value_kind:     hidden_dynamic_lds_size
    .group_segment_fixed_size: 0
    .kernarg_segment_align: 8
    .kernarg_segment_size: 456
    .language:       OpenCL C
    .language_version:
      - 2
      - 0
    .max_flat_workgroup_size: 512
    .name:           _Z6mk_fwd4Args
    .private_segment_fixed_size: 0
    .sgpr_count:     108
    .sgpr_spill_count: 99
    .symbol:         _Z6mk_fwd4Args.kd
    .uniform_work_group_size: 1
    .uses_dynamic_stack: false
    .vgpr_count:     256
    .vgpr_spill_count: 0
    .wavefront_size: 64
